# phase-2 implicit-filter epilogue regenerated straight-line: per-tile forward/backward branch instead of per-element EXEC diamonds, decay and row addresses once per column, wider stores
# speedup vs baseline: 1.0117x; 1.0117x over previous
; template <bool SWAP, class Epi, bool THIN = false> ...
;     ...
;     if (w < full * 8 * NT) { const int sr = w / (8 * NT), rem = w - sr * 8 * NT; nt = rem >> 3; mt = sr * 8 + (rem & 7); }
;     else { const int w2 = w - full * 8 * NT, rl = MT - full * 8; nt = w2 / rl; mt = full * 8 + (w2 - nt * rl); }
;     unsigned ap[4], bp[4];
; #pragma unroll
;     for (int i = 0; i < 4; ++i) {
;       const int r = (tid >> 3) + 64 * i;
;       const int cs = tid & 7;
;       const int c = ((cs ^ ((r >> 1) & 7)) << 3);
;       const int sub = 2 * mt + (r >> 7);
;       const int g = sub / tpg, ti = sub - g * tpg;
;       int rig = ti * step - halo + (r & 127); rig = rig < 0 ? 0 : (rig > grows - 1 ? grows - 1 : rig);
;       ap[i] = (unsigned)((g * a_gstride + a_goff + rig) * lda + c);
;       int br = nt * 256 + r; br = br > N - 1 ? N - 1 : br;
;       bp[i] = (unsigned)(br * K + c);
;     }
;     const bool have_next = false;
;     f32x4 acc[4][8];
; #pragma unroll
;     for (int m = 0; m < 4; ++m)
; #pragma unroll
;       for (int n = 0; n < 8; ++n) acc[m][n] = (f32x4){0.f, 0.f, 0.f, 0.f};
;     if (!pre_issued) {
; #pragma unroll
;       for (int i = 0; i < 4; ++i) { GLDS16(A + (size_t)ap[i], smem + tid * 16 + i * 8192); GLDS16(Bt + (size_t)bp[i], smem + 32768 + tid * 16 + i * 8192); }
;     ...
;       bf16x8 afA[4], afB[4], bfb[2][2];
; #pragma unroll
;       for (int m = 0; m < 4; ++m) afA[m] = *(const bf16x8*)(sa + m * 2048 + ((fq ^ swz) << 4));
; #pragma unroll
;       for (int n = 0; n < 2; ++n) bfb[0][n] = *(const bf16x8*)(sb + n * 2048 + ((fq ^ swz) << 4));
; #pragma unroll
;       for (int gq = 0; gq < 8; ++gq) {
;         const int ks = gq >> 2, nh = gq & 3;
;         if (gq < 7) {
;           const int ks2 = (gq + 1) >> 2, nh2 = (gq + 1) & 3;
; #pragma unroll
;           for (int n = 0; n < 2; ++n) bfb[(gq + 1) & 1][n] = *(const bf16x8*)(sb + (nh2 * 2 + n) * 2048 + (((ks2 * 4 + fq) ^ swz) << 4));
;         }
;         if (gq == 3) {
; #pragma unroll
;           for (int m = 0; m < 4; ++m) afB[m] = *(const bf16x8*)(sa + m * 2048 + (((4 + fq) ^ swz) << 4));
;         }
;         __builtin_amdgcn_sched_barrier(0);
; #pragma unroll
;         for (int m = 0; m < 4; ++m)
; #pragma unroll
;           for (int n = 0; n < 2; ++n) {
;             const bf16x8 av = ks ? afB[m] : afA[m];
.LBB0_496:
	s_add_i32 s4, s56, 0xffffff38
	s_ashr_i32 s5, s4, 31
	s_lshr_b32 s5, s5, 26
	s_add_i32 s4, s4, s5
	s_ashr_i32 s4, s4, 6
	s_lshl_b32 s5, s4, 4
	s_and_b32 s6, s57, 14
	s_or_b32 s5, s5, s6
	v_add_u32_e32 v2, s5, v141
	v_ashrrev_i32_e32 v3, 31, v2
	v_lshrrev_b32_e32 v3, 28, v3
	v_add_u32_e32 v4, s5, v144
	v_add_u32_e32 v3, v2, v3
	v_ashrrev_i32_e32 v5, 31, v4
	v_and_b32_e32 v3, -16, v3
	v_lshrrev_b32_e32 v5, 28, v5
	v_add_u32_e32 v6, s5, v147
	v_sub_u32_e32 v2, v2, v3
	v_add_u32_e32 v5, v4, v5
	v_ashrrev_i32_e32 v7, 31, v6
	v_lshl_or_b32 v3, v2, 7, v142
	v_and_b32_e32 v5, -16, v5
	v_lshrrev_b32_e32 v7, 28, v7
	v_add_u32_e32 v8, s5, v149
	s_lshl_b32 s4, s4, 11
	v_min_i32_e32 v3, 0x7ff, v3
	v_sub_u32_e32 v4, v4, v5
	v_add_u32_e32 v7, v6, v7
	v_ashrrev_i32_e32 v9, 31, v8
	s_sub_i32 s4, s59, s4
	v_lshlrev_b32_e32 v3, 6, v3
	v_cmp_lt_i32_e32 vcc, -1, v2
	v_lshl_or_b32 v5, v4, 7, v145
	v_and_b32_e32 v7, -16, v7
	v_lshrrev_b32_e32 v9, 28, v9
	s_and_b32 s4, s4, 0xffffff00
	v_cndmask_b32_e32 v2, 0, v3, vcc
	v_min_i32_e32 v5, 0x7ff, v5
	v_sub_u32_e32 v6, v6, v7
	v_add_u32_e32 v9, v8, v9
	v_or_b32_e32 v3, v2, v139
	v_add_u32_e32 v2, s4, v138
	v_lshlrev_b32_e32 v5, 6, v5
	v_cmp_lt_i32_e32 vcc, -1, v4
	v_lshl_or_b32 v7, v6, 7, v142
	v_and_b32_e32 v9, -16, v9
	v_min_i32_e32 v2, 0x7ff, v2
	v_cndmask_b32_e32 v4, 0, v5, vcc
	v_min_i32_e32 v7, 0x7ff, v7
	v_sub_u32_e32 v8, v8, v9
	v_lshlrev_b32_e32 v130, 1, v3
	v_readfirstlane_b32 s6, v140
	v_lshl_or_b32 v2, v2, 6, v139
	v_or_b32_e32 v5, v4, v139
	v_add_u32_e32 v4, s4, v143
	v_lshlrev_b32_e32 v7, 6, v7
	v_cmp_lt_i32_e32 vcc, -1, v6
	v_lshl_or_b32 v9, v8, 7, v150
	s_waitcnt lgkmcnt(0)
	v_lshl_add_u64 v[10:11], s[42:43], 0, v[130:131]
	s_mov_b32 m0, s6
	v_mov_b32_e32 v3, v131
	v_readfirstlane_b32 s6, v151
	v_min_i32_e32 v4, 0x7ff, v4
	v_cndmask_b32_e32 v6, 0, v7, vcc
	v_min_i32_e32 v9, 0x7ff, v9
	global_load_lds_dwordx4 v[10:11], off
	v_lshl_add_u64 v[2:3], v[2:3], 1, s[40:41]
	s_mov_b32 m0, s6
	v_lshlrev_b32_e32 v130, 1, v5
	v_readfirstlane_b32 s6, v152
	v_lshl_or_b32 v4, v4, 6, v139
	v_or_b32_e32 v7, v6, v139
	v_add_u32_e32 v6, s4, v146
	v_lshlrev_b32_e32 v9, 6, v9
	v_cmp_lt_i32_e32 vcc, -1, v8
	global_load_lds_dwordx4 v[2:3], off
	v_lshl_add_u64 v[2:3], s[42:43], 0, v[130:131]
	s_mov_b32 m0, s6
	v_mov_b32_e32 v5, v131
	v_readfirstlane_b32 s6, v153
	v_min_i32_e32 v6, 0x7ff, v6
	v_cndmask_b32_e32 v8, 0, v9, vcc
	global_load_lds_dwordx4 v[2:3], off
	v_lshl_add_u64 v[2:3], v[4:5], 1, s[40:41]
	s_mov_b32 m0, s6
	v_lshlrev_b32_e32 v130, 1, v7
	v_readfirstlane_b32 s6, v154
	v_lshl_or_b32 v6, v6, 6, v139
	v_or_b32_e32 v9, v8, v139
	v_add_u32_e32 v8, s4, v148
	global_load_lds_dwordx4 v[2:3], off
	v_lshl_add_u64 v[2:3], s[42:43], 0, v[130:131]
	s_mov_b32 m0, s6
	v_mov_b32_e32 v7, v131
	v_readfirstlane_b32 s6, v155
	v_min_i32_e32 v8, 0x7ff, v8
	global_load_lds_dwordx4 v[2:3], off
	v_lshl_add_u64 v[2:3], v[6:7], 1, s[40:41]
	s_mov_b32 m0, s6
	v_lshlrev_b32_e32 v130, 1, v9
	v_readfirstlane_b32 s6, v156
	v_lshl_or_b32 v8, v8, 6, v139
	global_load_lds_dwordx4 v[2:3], off
	v_lshl_add_u64 v[2:3], s[42:43], 0, v[130:131]
	s_mov_b32 m0, s6
	v_mov_b32_e32 v9, v131
	v_readfirstlane_b32 s6, v157
	global_load_lds_dwordx4 v[2:3], off
	v_lshl_add_u64 v[2:3], v[8:9], 1, s[40:41]
	s_mov_b32 m0, s6
	s_nop 0
	global_load_lds_dwordx4 v[2:3], off
	s_waitcnt vmcnt(0)
	s_barrier
	ds_read_b128 v[2:5], v158
	ds_read_b128 v[6:9], v158 offset:2048
	ds_read_b128 v[10:13], v158 offset:4096
	ds_read_b128 v[14:17], v158 offset:6144
	ds_read_b128 v[18:21], v159 offset:32768
	ds_read_b128 v[22:25], v159 offset:34816
	ds_read_b128 v[26:29], v159 offset:36864
	ds_read_b128 v[30:33], v159 offset:38912
	ds_read_b128 v[58:61], v159 offset:40960
	ds_read_b128 v[62:65], v159 offset:43008
	s_waitcnt lgkmcnt(0)
	v_mfma_f32_16x16x32_bf16 v[34:37], v[2:5], v[18:21], 0
	v_mfma_f32_16x16x32_bf16 v[38:41], v[2:5], v[22:25], 0
	v_mfma_f32_16x16x32_bf16 v[42:45], v[6:9], v[18:21], 0
	v_mfma_f32_16x16x32_bf16 v[46:49], v[6:9], v[22:25], 0
	v_mfma_f32_16x16x32_bf16 v[50:53], v[10:13], v[18:21], 0
	v_mfma_f32_16x16x32_bf16 v[54:57], v[10:13], v[22:25], 0
	v_mfma_f32_16x16x32_bf16 v[18:21], v[14:17], v[18:21], 0
	v_mfma_f32_16x16x32_bf16 v[22:25], v[14:17], v[22:25], 0
	v_mfma_f32_16x16x32_bf16 v[66:69], v[2:5], v[26:29], 0
	v_mfma_f32_16x16x32_bf16 v[74:77], v[6:9], v[26:29], 0
	v_mfma_f32_16x16x32_bf16 v[98:101], v[10:13], v[26:29], 0
	v_mfma_f32_16x16x32_bf16 v[106:109], v[14:17], v[26:29], 0
	ds_read_b128 v[26:29], v159 offset:45056
	ds_read_b128 v[82:85], v159 offset:47104
	v_mfma_f32_16x16x32_bf16 v[70:73], v[2:5], v[30:33], 0
	v_mfma_f32_16x16x32_bf16 v[78:81], v[6:9], v[30:33], 0
	v_mfma_f32_16x16x32_bf16 v[102:105], v[10:13], v[30:33], 0
	v_mfma_f32_16x16x32_bf16 v[110:113], v[14:17], v[30:33], 0
	ds_read_b128 v[30:33], v160 offset:32768
	ds_read_b128 v[86:89], v160 offset:34816
	ds_read_b128 v[186:189], v161
	ds_read_b128 v[190:193], v161 offset:2048
	ds_read_b128 v[194:197], v161 offset:4096
	ds_read_b128 v[198:201], v161 offset:6144
	v_mfma_f32_16x16x32_bf16 v[132:135], v[2:5], v[58:61], 0
	v_mfma_f32_16x16x32_bf16 v[162:165], v[2:5], v[62:65], 0
	v_mfma_f32_16x16x32_bf16 v[166:169], v[6:9], v[58:61], 0
	v_mfma_f32_16x16x32_bf16 v[170:173], v[6:9], v[62:65], 0
	v_mfma_f32_16x16x32_bf16 v[174:177], v[10:13], v[58:61], 0
	v_mfma_f32_16x16x32_bf16 v[178:181], v[10:13], v[62:65], 0
	v_mfma_f32_16x16x32_bf16 v[182:185], v[14:17], v[58:61], 0
	v_mfma_f32_16x16x32_bf16 v[202:205], v[14:17], v[62:65], 0
	s_waitcnt lgkmcnt(0)
; __device__ __forceinline__ bf16_t f2bf(float f) { return (bf16_t)(pack2(f, f) & 0xffffu); }
;   __device__ __forceinline__ void r4(int g, int rig, int col, f32x4 v) const {
;     const int c = col & 1023; const bool bwd = col >= 1024;
;     const float dec = fabsf(decay[c]);
;     bf16_t* rp = Rf + (size_t)c * 4096;
; #pragma unroll
;     for (int j = 0; j < 4; ++j) {
;       const int t = rig + j;
;       const float val = v[j] * __expf(-(float)t * (1.0f / 2047.0f) * dec);
;       if (!bwd) rp[2048 - t] = f2bf(val);
;       else if (t > 0) rp[2048 + t] = f2bf(val);
;       else rp[0] = 0;
;     }
;   }
; template <bool SWAP, class Epi, bool THIN = false> ...
;     ...
;     } else if constexpr (Epi::KIND == 1) {
; #pragma unroll
;       for (int m = 0; m < 4; ++m) {
;         const int rig = rig0 + rw + m * 16 + fq_e * 4;
; #pragma unroll
;         for (int n = 0; n < 8; ++n) {
;           const int col = nt * 256 + wc_e * 128 + n * 16 + fr_e;
;           if (col < N) epi.r4(g, rig, col, acc[m][n]);
;         }
;       }
	v_mfma_f32_16x16x32_bf16 v[214:217], v[10:13], v[26:29], 0
	v_mfma_f32_16x16x32_bf16 v[218:221], v[10:13], v[82:85], 0
	ds_read_b128 v[10:13], v160 offset:36864
	ds_read_b128 v[226:229], v160 offset:38912
	v_mfma_f32_16x16x32_bf16 v[206:209], v[2:5], v[26:29], 0
	v_mfma_f32_16x16x32_bf16 v[2:5], v[2:5], v[82:85], 0
	v_mfma_f32_16x16x32_bf16 v[210:213], v[6:9], v[26:29], 0
	v_mfma_f32_16x16x32_bf16 v[6:9], v[6:9], v[82:85], 0
	v_mfma_f32_16x16x32_bf16 v[222:225], v[14:17], v[26:29], 0
	v_mfma_f32_16x16x32_bf16 v[230:233], v[14:17], v[82:85], 0
	v_mfma_f32_16x16x32_bf16 v[126:129], v[186:189], v[30:33], v[34:37]
	ds_read_b128 v[14:17], v160 offset:40960
	s_nop 1
	ds_read_b128 v[34:37], v160 offset:43008
	v_mfma_f32_16x16x32_bf16 v[122:125], v[186:189], v[86:89], v[38:41]
	v_mfma_f32_16x16x32_bf16 v[94:97], v[190:193], v[30:33], v[42:45]
	v_mfma_f32_16x16x32_bf16 v[90:93], v[190:193], v[86:89], v[46:49]
	v_mfma_f32_16x16x32_bf16 v[62:65], v[194:197], v[30:33], v[50:53]
	v_mfma_f32_16x16x32_bf16 v[58:61], v[194:197], v[86:89], v[54:57]
	v_mfma_f32_16x16x32_bf16 v[30:33], v[198:201], v[30:33], v[18:21]
	v_mfma_f32_16x16x32_bf16 v[26:29], v[198:201], v[86:89], v[22:25]
	ds_read_b128 v[234:237], v160 offset:45056
	ds_read_b128 v[238:241], v160 offset:47104
	s_waitcnt lgkmcnt(0)
	v_mfma_f32_16x16x32_bf16 v[118:121], v[186:189], v[10:13], v[66:69]
	v_mfma_f32_16x16x32_bf16 v[114:117], v[186:189], v[226:229], v[70:73]
	v_mfma_f32_16x16x32_bf16 v[86:89], v[190:193], v[10:13], v[74:77]
	v_mfma_f32_16x16x32_bf16 v[82:85], v[190:193], v[226:229], v[78:81]
	v_mfma_f32_16x16x32_bf16 v[54:57], v[194:197], v[10:13], v[98:101]
	v_mfma_f32_16x16x32_bf16 v[50:53], v[194:197], v[226:229], v[102:105]
	v_mfma_f32_16x16x32_bf16 v[22:25], v[198:201], v[10:13], v[106:109]
	v_mfma_f32_16x16x32_bf16 v[18:21], v[198:201], v[226:229], v[110:113]
	v_mfma_f32_16x16x32_bf16 v[110:113], v[186:189], v[14:17], v[132:135]
	v_mfma_f32_16x16x32_bf16 v[106:109], v[186:189], v[34:37], v[162:165]
	v_mfma_f32_16x16x32_bf16 v[78:81], v[190:193], v[14:17], v[166:169]
	v_mfma_f32_16x16x32_bf16 v[74:77], v[190:193], v[34:37], v[170:173]
	v_mfma_f32_16x16x32_bf16 v[46:49], v[194:197], v[14:17], v[174:177]
	v_mfma_f32_16x16x32_bf16 v[42:45], v[194:197], v[34:37], v[178:181]
	v_mfma_f32_16x16x32_bf16 v[14:17], v[198:201], v[14:17], v[182:185]
	v_mfma_f32_16x16x32_bf16 v[10:13], v[198:201], v[34:37], v[202:205]
	v_mov_b32_e32 v132, v1
	s_waitcnt vmcnt(0)
	s_barrier
	v_mfma_f32_16x16x32_bf16 v[98:101], v[186:189], v[238:241], v[2:5]
	s_nop 2
	v_ashrrev_i32_e32 v3, 8, v132
	v_add_u32_e32 v3, s5, v3
	v_ashrrev_i32_e32 v4, 31, v3
	v_lshrrev_b32_e32 v4, 28, v4
	v_lshlrev_b32_e32 v5, 7, v3
	v_add_lshl_u32 v3, v3, v4, 7
	v_and_b32_e32 v3, 0xfffff800, v3
	v_sub_u32_e32 v133, v5, v3
	v_lshrrev_b32_e32 v3, 1, v132
	v_lshrrev_b32_e32 v4, 2, v132
	v_and_b32_e32 v3, 64, v3
	v_and_b32_e32 v4, 12, v4
	v_or3_b32 v130, v3, v4, v133
	v_and_b32_e32 v2, 15, v132
	v_lshlrev_b32_e32 v3, 1, v132
	v_cvt_f32_i32_e32 v132, v130
	v_and_b32_e32 v3, 0x80, v3
	v_or3_b32 v162, v2, v3, s4
	v_cmp_gt_i32_e64 s[4:5], 0, v133
	v_mul_f32_e32 v167, 0xba001002, v132
	v_or_b32_e32 v132, 1, v130
	v_cvt_f32_i32_e32 v132, v132
	v_or_b32_e32 v133, 2, v130
	v_or_b32_e32 v136, 3, v130
	v_cvt_f32_i32_e32 v133, v133
	v_cvt_f32_i32_e32 v136, v136
	v_mfma_f32_16x16x32_bf16 v[102:105], v[186:189], v[234:237], v[206:209]
	v_sub_u32_e32 v134, 0x800, v130
	v_mul_f32_e32 v166, 0xba001002, v132
	v_and_b32_e32 v132, 0x38f, v162
	v_mfma_f32_16x16x32_bf16 v[70:73], v[190:193], v[234:237], v[210:213]
	v_ashrrev_i32_e32 v135, 31, v134
	v_cmp_gt_i32_e64 s[26:27], 1, v130
	v_mul_f32_e32 v165, 0xba001002, v133
	v_mfma_f32_16x16x32_bf16 v[66:69], v[190:193], v[238:241], v[6:9]
	v_cmp_gt_i32_e64 s[24:25], -1, v130
	v_mul_f32_e32 v164, 0xba001002, v136
	v_cmp_gt_i32_e64 s[22:23], -2, v130
	v_mfma_f32_16x16x32_bf16 v[38:41], v[194:197], v[234:237], v[214:217]
	v_cmp_gt_i32_e64 s[6:7], s61, v162
	v_lshlrev_b32_e32 v163, 2, v132
	v_lshlrev_b32_e32 v132, 13, v132
	v_mfma_f32_16x16x32_bf16 v[34:37], v[194:197], v[238:241], v[218:221]
	v_mfma_f32_16x16x32_bf16 v[6:9], v[198:201], v[234:237], v[222:225]
	v_mfma_f32_16x16x32_bf16 v[2:5], v[198:201], v[238:241], v[230:233]
	v_and_b32_e32 v132, 0x38f, v162
	v_mov_b32_e32 v133, v132
	v_lshlrev_b32_e32 v204, 2, v133
	global_load_dword v164, v204, s[48:49]
	v_lshlrev_b32_e32 v204, 13, v133
	v_mov_b32_e32 v205, 0
	v_lshl_add_u64 v[172:173], s[44:45], 0, v[204:205]
	v_or_b32_e32 v133, 16, v132
	v_lshlrev_b32_e32 v204, 2, v133
	global_load_dword v165, v204, s[48:49]
	v_lshlrev_b32_e32 v204, 13, v133
	v_mov_b32_e32 v205, 0
	v_lshl_add_u64 v[174:175], s[44:45], 0, v[204:205]
	v_or_b32_e32 v133, 32, v132
	v_lshlrev_b32_e32 v204, 2, v133
	global_load_dword v166, v204, s[48:49]
	v_lshlrev_b32_e32 v204, 13, v133
	v_mov_b32_e32 v205, 0
	v_lshl_add_u64 v[176:177], s[44:45], 0, v[204:205]
	v_or_b32_e32 v133, 48, v132
	v_lshlrev_b32_e32 v204, 2, v133
	global_load_dword v167, v204, s[48:49]
	v_lshlrev_b32_e32 v204, 13, v133
	v_mov_b32_e32 v205, 0
	v_lshl_add_u64 v[178:179], s[44:45], 0, v[204:205]
	v_or_b32_e32 v133, 64, v132
	v_lshlrev_b32_e32 v204, 2, v133
	global_load_dword v168, v204, s[48:49]
	v_lshlrev_b32_e32 v204, 13, v133
	v_mov_b32_e32 v205, 0
	v_lshl_add_u64 v[180:181], s[44:45], 0, v[204:205]
	v_or_b32_e32 v133, 80, v132
	v_lshlrev_b32_e32 v204, 2, v133
	global_load_dword v169, v204, s[48:49]
	v_lshlrev_b32_e32 v204, 13, v133
	v_mov_b32_e32 v205, 0
	v_lshl_add_u64 v[182:183], s[44:45], 0, v[204:205]
	v_or_b32_e32 v133, 96, v132
	v_lshlrev_b32_e32 v204, 2, v133
	global_load_dword v170, v204, s[48:49]
	v_lshlrev_b32_e32 v204, 13, v133
	v_mov_b32_e32 v205, 0
	v_lshl_add_u64 v[184:185], s[44:45], 0, v[204:205]
	v_or_b32_e32 v133, 112, v132
	v_lshlrev_b32_e32 v204, 2, v133
	global_load_dword v171, v204, s[48:49]
	v_lshlrev_b32_e32 v204, 13, v133
	v_mov_b32_e32 v205, 0
	v_lshl_add_u64 v[186:187], s[44:45], 0, v[204:205]
	v_mov_b32_e32 v209, 0
	v_cmp_eq_u32_e64 s[12:13], 0, v130
	v_readfirstlane_b32 s10, v162
	s_waitcnt vmcnt(0)
	s_cmp_lt_u32 s10, 0x400
	s_cbranch_scc0 .Lfilt_bwd
; __device__ __forceinline__ bf16_t f2bf(float f) { return (bf16_t)(pack2(f, f) & 0xffffu); }
;   __device__ __forceinline__ void r4(int g, int rig, int col, f32x4 v) const {
;     const int c = col & 1023; const bool bwd = col >= 1024;
;     const float dec = fabsf(decay[c]);
;     bf16_t* rp = Rf + (size_t)c * 4096;
; #pragma unroll
;     for (int j = 0; j < 4; ++j) {
;       const int t = rig + j;
;       const float val = v[j] * __expf(-(float)t * (1.0f / 2047.0f) * dec);
;       if (!bwd) rp[2048 - t] = f2bf(val);
;       else if (t > 0) rp[2048 + t] = f2bf(val);
;       else rp[0] = 0;
;     }
;   }
	v_mov_b32_e32 v206, v130
	v_cvt_f32_i32_e32 v188, v206
	v_or_b32_e32 v204, 1, v206
	v_cvt_f32_i32_e32 v189, v204
	v_or_b32_e32 v204, 2, v206
	v_cvt_f32_i32_e32 v190, v204
	v_or_b32_e32 v204, 3, v206
	v_cvt_f32_i32_e32 v191, v204
	v_mul_f32_e32 v188, 0xba001002, v188
	v_mul_f32_e32 v189, 0xba001002, v189
	v_mul_f32_e32 v190, 0xba001002, v190
	v_mul_f32_e32 v191, 0xba001002, v191
	v_sub_u32_e32 v208, 0x800, v206
	v_lshlrev_b32_e32 v208, 1, v208
	v_mul_f32_e64 v192, v188, |v164|
	v_mul_f32_e64 v193, v189, |v164|
	v_mul_f32_e64 v194, v190, |v164|
	v_mul_f32_e64 v195, v191, |v164|
	v_mul_f32_e32 v192, 0x3fb8aa3b, v192
	v_mul_f32_e32 v193, 0x3fb8aa3b, v193
	v_mul_f32_e32 v194, 0x3fb8aa3b, v194
	v_mul_f32_e32 v195, 0x3fb8aa3b, v195
	v_exp_f32_e32 v192, v192
	v_exp_f32_e32 v193, v193
	v_exp_f32_e32 v194, v194
	v_exp_f32_e32 v195, v195
	s_nop 0
	v_mul_f32_e32 v196, v126, v192
	v_mul_f32_e32 v197, v127, v193
	v_mul_f32_e32 v198, v128, v194
	v_mul_f32_e32 v199, v129, v195
	v_lshl_add_u64 v[202:203], v[172:173], 0, v[208:209]
	v_cvt_pk_bf16_f32 v200, v196, v196
	v_cvt_pk_bf16_f32 v201, v198, v197
	v_cvt_pk_bf16_f32 v204, v199, v199
	s_nop 0
	global_store_short v[202:203], v200, off
	global_store_dword v[202:203], v201, off offset:-4
	global_store_short v[202:203], v204, off offset:-6
	v_mul_f32_e64 v192, v188, |v165|
	v_mul_f32_e64 v193, v189, |v165|
	v_mul_f32_e64 v194, v190, |v165|
	v_mul_f32_e64 v195, v191, |v165|
	v_mul_f32_e32 v192, 0x3fb8aa3b, v192
	v_mul_f32_e32 v193, 0x3fb8aa3b, v193
	v_mul_f32_e32 v194, 0x3fb8aa3b, v194
	v_mul_f32_e32 v195, 0x3fb8aa3b, v195
	v_exp_f32_e32 v192, v192
	v_exp_f32_e32 v193, v193
	v_exp_f32_e32 v194, v194
	v_exp_f32_e32 v195, v195
	s_nop 0
	v_mul_f32_e32 v196, v122, v192
	v_mul_f32_e32 v197, v123, v193
	v_mul_f32_e32 v198, v124, v194
	v_mul_f32_e32 v199, v125, v195
	v_lshl_add_u64 v[202:203], v[174:175], 0, v[208:209]
	v_cvt_pk_bf16_f32 v200, v196, v196
	v_cvt_pk_bf16_f32 v201, v198, v197
	v_cvt_pk_bf16_f32 v204, v199, v199
	s_nop 0
	global_store_short v[202:203], v200, off
	global_store_dword v[202:203], v201, off offset:-4
	global_store_short v[202:203], v204, off offset:-6
	v_mul_f32_e64 v192, v188, |v166|
	v_mul_f32_e64 v193, v189, |v166|
	v_mul_f32_e64 v194, v190, |v166|
	v_mul_f32_e64 v195, v191, |v166|
	v_mul_f32_e32 v192, 0x3fb8aa3b, v192
	v_mul_f32_e32 v193, 0x3fb8aa3b, v193
	v_mul_f32_e32 v194, 0x3fb8aa3b, v194
	v_mul_f32_e32 v195, 0x3fb8aa3b, v195
	v_exp_f32_e32 v192, v192
	v_exp_f32_e32 v193, v193
	v_exp_f32_e32 v194, v194
	v_exp_f32_e32 v195, v195
	s_nop 0
	v_mul_f32_e32 v196, v118, v192
	v_mul_f32_e32 v197, v119, v193
	v_mul_f32_e32 v198, v120, v194
	v_mul_f32_e32 v199, v121, v195
	v_lshl_add_u64 v[202:203], v[176:177], 0, v[208:209]
	v_cvt_pk_bf16_f32 v200, v196, v196
	v_cvt_pk_bf16_f32 v201, v198, v197
	v_cvt_pk_bf16_f32 v204, v199, v199
	s_nop 0
	global_store_short v[202:203], v200, off
	global_store_dword v[202:203], v201, off offset:-4
	global_store_short v[202:203], v204, off offset:-6
	v_mul_f32_e64 v192, v188, |v167|
	v_mul_f32_e64 v193, v189, |v167|
	v_mul_f32_e64 v194, v190, |v167|
	v_mul_f32_e64 v195, v191, |v167|
	v_mul_f32_e32 v192, 0x3fb8aa3b, v192
	v_mul_f32_e32 v193, 0x3fb8aa3b, v193
	v_mul_f32_e32 v194, 0x3fb8aa3b, v194
	v_mul_f32_e32 v195, 0x3fb8aa3b, v195
	v_exp_f32_e32 v192, v192
	v_exp_f32_e32 v193, v193
	v_exp_f32_e32 v194, v194
	v_exp_f32_e32 v195, v195
	s_nop 0
	v_mul_f32_e32 v196, v114, v192
	v_mul_f32_e32 v197, v115, v193
	v_mul_f32_e32 v198, v116, v194
	v_mul_f32_e32 v199, v117, v195
	v_lshl_add_u64 v[202:203], v[178:179], 0, v[208:209]
	v_cvt_pk_bf16_f32 v200, v196, v196
	v_cvt_pk_bf16_f32 v201, v198, v197
	v_cvt_pk_bf16_f32 v204, v199, v199
	s_nop 0
	global_store_short v[202:203], v200, off
	global_store_dword v[202:203], v201, off offset:-4
	global_store_short v[202:203], v204, off offset:-6
	v_mul_f32_e64 v192, v188, |v168|
	v_mul_f32_e64 v193, v189, |v168|
	v_mul_f32_e64 v194, v190, |v168|
	v_mul_f32_e64 v195, v191, |v168|
	v_mul_f32_e32 v192, 0x3fb8aa3b, v192
	v_mul_f32_e32 v193, 0x3fb8aa3b, v193
	v_mul_f32_e32 v194, 0x3fb8aa3b, v194
	v_mul_f32_e32 v195, 0x3fb8aa3b, v195
	v_exp_f32_e32 v192, v192
	v_exp_f32_e32 v193, v193
	v_exp_f32_e32 v194, v194
	v_exp_f32_e32 v195, v195
	s_nop 0
	v_mul_f32_e32 v196, v110, v192
	v_mul_f32_e32 v197, v111, v193
	v_mul_f32_e32 v198, v112, v194
	v_mul_f32_e32 v199, v113, v195
	v_lshl_add_u64 v[202:203], v[180:181], 0, v[208:209]
	v_cvt_pk_bf16_f32 v200, v196, v196
	v_cvt_pk_bf16_f32 v201, v198, v197
	v_cvt_pk_bf16_f32 v204, v199, v199
	s_nop 0
	global_store_short v[202:203], v200, off
	global_store_dword v[202:203], v201, off offset:-4
	global_store_short v[202:203], v204, off offset:-6
	v_mul_f32_e64 v192, v188, |v169|
	v_mul_f32_e64 v193, v189, |v169|
	v_mul_f32_e64 v194, v190, |v169|
	v_mul_f32_e64 v195, v191, |v169|
	v_mul_f32_e32 v192, 0x3fb8aa3b, v192
	v_mul_f32_e32 v193, 0x3fb8aa3b, v193
	v_mul_f32_e32 v194, 0x3fb8aa3b, v194
	v_mul_f32_e32 v195, 0x3fb8aa3b, v195
	v_exp_f32_e32 v192, v192
	v_exp_f32_e32 v193, v193
	v_exp_f32_e32 v194, v194
	v_exp_f32_e32 v195, v195
	s_nop 0
	v_mul_f32_e32 v196, v106, v192
	v_mul_f32_e32 v197, v107, v193
	v_mul_f32_e32 v198, v108, v194
	v_mul_f32_e32 v199, v109, v195
	v_lshl_add_u64 v[202:203], v[182:183], 0, v[208:209]
	v_cvt_pk_bf16_f32 v200, v196, v196
	v_cvt_pk_bf16_f32 v201, v198, v197
	v_cvt_pk_bf16_f32 v204, v199, v199
	s_nop 0
	global_store_short v[202:203], v200, off
	global_store_dword v[202:203], v201, off offset:-4
	global_store_short v[202:203], v204, off offset:-6
	v_mul_f32_e64 v192, v188, |v170|
	v_mul_f32_e64 v193, v189, |v170|
	v_mul_f32_e64 v194, v190, |v170|
; __device__ __forceinline__ bf16_t f2bf(float f) { return (bf16_t)(pack2(f, f) & 0xffffu); }
;   __device__ __forceinline__ void r4(int g, int rig, int col, f32x4 v) const {
;     const int c = col & 1023; const bool bwd = col >= 1024;
;     const float dec = fabsf(decay[c]);
;     bf16_t* rp = Rf + (size_t)c * 4096;
; #pragma unroll
;     for (int j = 0; j < 4; ++j) {
;       const int t = rig + j;
;       const float val = v[j] * __expf(-(float)t * (1.0f / 2047.0f) * dec);
;       if (!bwd) rp[2048 - t] = f2bf(val);
;       else if (t > 0) rp[2048 + t] = f2bf(val);
;       else rp[0] = 0;
;     }
;   }
	v_mul_f32_e64 v195, v191, |v170|
	v_mul_f32_e32 v192, 0x3fb8aa3b, v192
	v_mul_f32_e32 v193, 0x3fb8aa3b, v193
	v_mul_f32_e32 v194, 0x3fb8aa3b, v194
	v_mul_f32_e32 v195, 0x3fb8aa3b, v195
	v_exp_f32_e32 v192, v192
	v_exp_f32_e32 v193, v193
	v_exp_f32_e32 v194, v194
	v_exp_f32_e32 v195, v195
	s_nop 0
	v_mul_f32_e32 v196, v102, v192
	v_mul_f32_e32 v197, v103, v193
	v_mul_f32_e32 v198, v104, v194
	v_mul_f32_e32 v199, v105, v195
	v_lshl_add_u64 v[202:203], v[184:185], 0, v[208:209]
	v_cvt_pk_bf16_f32 v200, v196, v196
	v_cvt_pk_bf16_f32 v201, v198, v197
	v_cvt_pk_bf16_f32 v204, v199, v199
	s_nop 0
	global_store_short v[202:203], v200, off
	global_store_dword v[202:203], v201, off offset:-4
	global_store_short v[202:203], v204, off offset:-6
	v_mul_f32_e64 v192, v188, |v171|
	v_mul_f32_e64 v193, v189, |v171|
	v_mul_f32_e64 v194, v190, |v171|
	v_mul_f32_e64 v195, v191, |v171|
	v_mul_f32_e32 v192, 0x3fb8aa3b, v192
	v_mul_f32_e32 v193, 0x3fb8aa3b, v193
	v_mul_f32_e32 v194, 0x3fb8aa3b, v194
	v_mul_f32_e32 v195, 0x3fb8aa3b, v195
	v_exp_f32_e32 v192, v192
	v_exp_f32_e32 v193, v193
	v_exp_f32_e32 v194, v194
	v_exp_f32_e32 v195, v195
	s_nop 0
	v_mul_f32_e32 v196, v98, v192
	v_mul_f32_e32 v197, v99, v193
	v_mul_f32_e32 v198, v100, v194
	v_mul_f32_e32 v199, v101, v195
	v_lshl_add_u64 v[202:203], v[186:187], 0, v[208:209]
	v_cvt_pk_bf16_f32 v200, v196, v196
	v_cvt_pk_bf16_f32 v201, v198, v197
	v_cvt_pk_bf16_f32 v204, v199, v199
	s_nop 0
	global_store_short v[202:203], v200, off
	global_store_dword v[202:203], v201, off offset:-4
	global_store_short v[202:203], v204, off offset:-6
	v_or_b32_e32 v206, 16, v130
	v_cvt_f32_i32_e32 v188, v206
	v_or_b32_e32 v204, 1, v206
	v_cvt_f32_i32_e32 v189, v204
	v_or_b32_e32 v204, 2, v206
	v_cvt_f32_i32_e32 v190, v204
	v_or_b32_e32 v204, 3, v206
	v_cvt_f32_i32_e32 v191, v204
	v_mul_f32_e32 v188, 0xba001002, v188
	v_mul_f32_e32 v189, 0xba001002, v189
	v_mul_f32_e32 v190, 0xba001002, v190
	v_mul_f32_e32 v191, 0xba001002, v191
	v_sub_u32_e32 v208, 0x800, v206
	v_lshlrev_b32_e32 v208, 1, v208
	v_mul_f32_e64 v192, v188, |v164|
	v_mul_f32_e64 v193, v189, |v164|
	v_mul_f32_e64 v194, v190, |v164|
	v_mul_f32_e64 v195, v191, |v164|
	v_mul_f32_e32 v192, 0x3fb8aa3b, v192
	v_mul_f32_e32 v193, 0x3fb8aa3b, v193
	v_mul_f32_e32 v194, 0x3fb8aa3b, v194
	v_mul_f32_e32 v195, 0x3fb8aa3b, v195
	v_exp_f32_e32 v192, v192
	v_exp_f32_e32 v193, v193
	v_exp_f32_e32 v194, v194
	v_exp_f32_e32 v195, v195
	s_nop 0
	v_mul_f32_e32 v196, v94, v192
	v_mul_f32_e32 v197, v95, v193
	v_mul_f32_e32 v198, v96, v194
	v_mul_f32_e32 v199, v97, v195
	v_lshl_add_u64 v[202:203], v[172:173], 0, v[208:209]
	v_cvt_pk_bf16_f32 v200, v196, v196
	v_cvt_pk_bf16_f32 v201, v198, v197
	v_cvt_pk_bf16_f32 v204, v199, v199
	s_nop 0
	global_store_short v[202:203], v200, off
	global_store_dword v[202:203], v201, off offset:-4
	global_store_short v[202:203], v204, off offset:-6
	v_mul_f32_e64 v192, v188, |v165|
	v_mul_f32_e64 v193, v189, |v165|
	v_mul_f32_e64 v194, v190, |v165|
	v_mul_f32_e64 v195, v191, |v165|
	v_mul_f32_e32 v192, 0x3fb8aa3b, v192
	v_mul_f32_e32 v193, 0x3fb8aa3b, v193
	v_mul_f32_e32 v194, 0x3fb8aa3b, v194
	v_mul_f32_e32 v195, 0x3fb8aa3b, v195
	v_exp_f32_e32 v192, v192
	v_exp_f32_e32 v193, v193
	v_exp_f32_e32 v194, v194
	v_exp_f32_e32 v195, v195
	s_nop 0
	v_mul_f32_e32 v196, v90, v192
	v_mul_f32_e32 v197, v91, v193
	v_mul_f32_e32 v198, v92, v194
	v_mul_f32_e32 v199, v93, v195
	v_lshl_add_u64 v[202:203], v[174:175], 0, v[208:209]
	v_cvt_pk_bf16_f32 v200, v196, v196
	v_cvt_pk_bf16_f32 v201, v198, v197
	v_cvt_pk_bf16_f32 v204, v199, v199
	s_nop 0
	global_store_short v[202:203], v200, off
	global_store_dword v[202:203], v201, off offset:-4
	global_store_short v[202:203], v204, off offset:-6
	v_mul_f32_e64 v192, v188, |v166|
	v_mul_f32_e64 v193, v189, |v166|
	v_mul_f32_e64 v194, v190, |v166|
	v_mul_f32_e64 v195, v191, |v166|
	v_mul_f32_e32 v192, 0x3fb8aa3b, v192
	v_mul_f32_e32 v193, 0x3fb8aa3b, v193
	v_mul_f32_e32 v194, 0x3fb8aa3b, v194
	v_mul_f32_e32 v195, 0x3fb8aa3b, v195
	v_exp_f32_e32 v192, v192
	v_exp_f32_e32 v193, v193
	v_exp_f32_e32 v194, v194
	v_exp_f32_e32 v195, v195
	s_nop 0
	v_mul_f32_e32 v196, v86, v192
	v_mul_f32_e32 v197, v87, v193
	v_mul_f32_e32 v198, v88, v194
	v_mul_f32_e32 v199, v89, v195
	v_lshl_add_u64 v[202:203], v[176:177], 0, v[208:209]
	v_cvt_pk_bf16_f32 v200, v196, v196
	v_cvt_pk_bf16_f32 v201, v198, v197
	v_cvt_pk_bf16_f32 v204, v199, v199
	s_nop 0
	global_store_short v[202:203], v200, off
	global_store_dword v[202:203], v201, off offset:-4
	global_store_short v[202:203], v204, off offset:-6
	v_mul_f32_e64 v192, v188, |v167|
	v_mul_f32_e64 v193, v189, |v167|
	v_mul_f32_e64 v194, v190, |v167|
	v_mul_f32_e64 v195, v191, |v167|
	v_mul_f32_e32 v192, 0x3fb8aa3b, v192
	v_mul_f32_e32 v193, 0x3fb8aa3b, v193
	v_mul_f32_e32 v194, 0x3fb8aa3b, v194
	v_mul_f32_e32 v195, 0x3fb8aa3b, v195
	v_exp_f32_e32 v192, v192
	v_exp_f32_e32 v193, v193
	v_exp_f32_e32 v194, v194
	v_exp_f32_e32 v195, v195
	s_nop 0
	v_mul_f32_e32 v196, v82, v192
	v_mul_f32_e32 v197, v83, v193
	v_mul_f32_e32 v198, v84, v194
	v_mul_f32_e32 v199, v85, v195
	v_lshl_add_u64 v[202:203], v[178:179], 0, v[208:209]
	v_cvt_pk_bf16_f32 v200, v196, v196
	v_cvt_pk_bf16_f32 v201, v198, v197
	v_cvt_pk_bf16_f32 v204, v199, v199
	s_nop 0
	global_store_short v[202:203], v200, off
	global_store_dword v[202:203], v201, off offset:-4
	global_store_short v[202:203], v204, off offset:-6
	v_mul_f32_e64 v192, v188, |v168|
	v_mul_f32_e64 v193, v189, |v168|
	v_mul_f32_e64 v194, v190, |v168|
	v_mul_f32_e64 v195, v191, |v168|
	v_mul_f32_e32 v192, 0x3fb8aa3b, v192
	v_mul_f32_e32 v193, 0x3fb8aa3b, v193
	v_mul_f32_e32 v194, 0x3fb8aa3b, v194
; __device__ __forceinline__ bf16_t f2bf(float f) { return (bf16_t)(pack2(f, f) & 0xffffu); }
;   __device__ __forceinline__ void r4(int g, int rig, int col, f32x4 v) const {
;     const int c = col & 1023; const bool bwd = col >= 1024;
;     const float dec = fabsf(decay[c]);
;     bf16_t* rp = Rf + (size_t)c * 4096;
; #pragma unroll
;     for (int j = 0; j < 4; ++j) {
;       const int t = rig + j;
;       const float val = v[j] * __expf(-(float)t * (1.0f / 2047.0f) * dec);
;       if (!bwd) rp[2048 - t] = f2bf(val);
;       else if (t > 0) rp[2048 + t] = f2bf(val);
;       else rp[0] = 0;
;     }
;   }
	v_mul_f32_e32 v195, 0x3fb8aa3b, v195
	v_exp_f32_e32 v192, v192
	v_exp_f32_e32 v193, v193
	v_exp_f32_e32 v194, v194
	v_exp_f32_e32 v195, v195
	s_nop 0
	v_mul_f32_e32 v196, v78, v192
	v_mul_f32_e32 v197, v79, v193
	v_mul_f32_e32 v198, v80, v194
	v_mul_f32_e32 v199, v81, v195
	v_lshl_add_u64 v[202:203], v[180:181], 0, v[208:209]
	v_cvt_pk_bf16_f32 v200, v196, v196
	v_cvt_pk_bf16_f32 v201, v198, v197
	v_cvt_pk_bf16_f32 v204, v199, v199
	s_nop 0
	global_store_short v[202:203], v200, off
	global_store_dword v[202:203], v201, off offset:-4
	global_store_short v[202:203], v204, off offset:-6
	v_mul_f32_e64 v192, v188, |v169|
	v_mul_f32_e64 v193, v189, |v169|
	v_mul_f32_e64 v194, v190, |v169|
	v_mul_f32_e64 v195, v191, |v169|
	v_mul_f32_e32 v192, 0x3fb8aa3b, v192
	v_mul_f32_e32 v193, 0x3fb8aa3b, v193
	v_mul_f32_e32 v194, 0x3fb8aa3b, v194
	v_mul_f32_e32 v195, 0x3fb8aa3b, v195
	v_exp_f32_e32 v192, v192
	v_exp_f32_e32 v193, v193
	v_exp_f32_e32 v194, v194
	v_exp_f32_e32 v195, v195
	s_nop 0
	v_mul_f32_e32 v196, v74, v192
	v_mul_f32_e32 v197, v75, v193
	v_mul_f32_e32 v198, v76, v194
	v_mul_f32_e32 v199, v77, v195
	v_lshl_add_u64 v[202:203], v[182:183], 0, v[208:209]
	v_cvt_pk_bf16_f32 v200, v196, v196
	v_cvt_pk_bf16_f32 v201, v198, v197
	v_cvt_pk_bf16_f32 v204, v199, v199
	s_nop 0
	global_store_short v[202:203], v200, off
	global_store_dword v[202:203], v201, off offset:-4
	global_store_short v[202:203], v204, off offset:-6
	v_mul_f32_e64 v192, v188, |v170|
	v_mul_f32_e64 v193, v189, |v170|
	v_mul_f32_e64 v194, v190, |v170|
	v_mul_f32_e64 v195, v191, |v170|
	v_mul_f32_e32 v192, 0x3fb8aa3b, v192
	v_mul_f32_e32 v193, 0x3fb8aa3b, v193
	v_mul_f32_e32 v194, 0x3fb8aa3b, v194
	v_mul_f32_e32 v195, 0x3fb8aa3b, v195
	v_exp_f32_e32 v192, v192
	v_exp_f32_e32 v193, v193
	v_exp_f32_e32 v194, v194
	v_exp_f32_e32 v195, v195
	s_nop 0
	v_mul_f32_e32 v196, v70, v192
	v_mul_f32_e32 v197, v71, v193
	v_mul_f32_e32 v198, v72, v194
	v_mul_f32_e32 v199, v73, v195
	v_lshl_add_u64 v[202:203], v[184:185], 0, v[208:209]
	v_cvt_pk_bf16_f32 v200, v196, v196
	v_cvt_pk_bf16_f32 v201, v198, v197
	v_cvt_pk_bf16_f32 v204, v199, v199
	s_nop 0
	global_store_short v[202:203], v200, off
	global_store_dword v[202:203], v201, off offset:-4
	global_store_short v[202:203], v204, off offset:-6
	v_mul_f32_e64 v192, v188, |v171|
	v_mul_f32_e64 v193, v189, |v171|
	v_mul_f32_e64 v194, v190, |v171|
	v_mul_f32_e64 v195, v191, |v171|
	v_mul_f32_e32 v192, 0x3fb8aa3b, v192
	v_mul_f32_e32 v193, 0x3fb8aa3b, v193
	v_mul_f32_e32 v194, 0x3fb8aa3b, v194
	v_mul_f32_e32 v195, 0x3fb8aa3b, v195
	v_exp_f32_e32 v192, v192
	v_exp_f32_e32 v193, v193
	v_exp_f32_e32 v194, v194
	v_exp_f32_e32 v195, v195
	s_nop 0
	v_mul_f32_e32 v196, v66, v192
	v_mul_f32_e32 v197, v67, v193
	v_mul_f32_e32 v198, v68, v194
	v_mul_f32_e32 v199, v69, v195
	v_lshl_add_u64 v[202:203], v[186:187], 0, v[208:209]
	v_cvt_pk_bf16_f32 v200, v196, v196
	v_cvt_pk_bf16_f32 v201, v198, v197
	v_cvt_pk_bf16_f32 v204, v199, v199
	s_nop 0
	global_store_short v[202:203], v200, off
	global_store_dword v[202:203], v201, off offset:-4
	global_store_short v[202:203], v204, off offset:-6
	v_or_b32_e32 v206, 32, v130
	v_cvt_f32_i32_e32 v188, v206
	v_or_b32_e32 v204, 1, v206
	v_cvt_f32_i32_e32 v189, v204
	v_or_b32_e32 v204, 2, v206
	v_cvt_f32_i32_e32 v190, v204
	v_or_b32_e32 v204, 3, v206
	v_cvt_f32_i32_e32 v191, v204
	v_mul_f32_e32 v188, 0xba001002, v188
	v_mul_f32_e32 v189, 0xba001002, v189
	v_mul_f32_e32 v190, 0xba001002, v190
	v_mul_f32_e32 v191, 0xba001002, v191
	v_sub_u32_e32 v208, 0x800, v206
	v_lshlrev_b32_e32 v208, 1, v208
	v_mul_f32_e64 v192, v188, |v164|
	v_mul_f32_e64 v193, v189, |v164|
	v_mul_f32_e64 v194, v190, |v164|
	v_mul_f32_e64 v195, v191, |v164|
	v_mul_f32_e32 v192, 0x3fb8aa3b, v192
	v_mul_f32_e32 v193, 0x3fb8aa3b, v193
	v_mul_f32_e32 v194, 0x3fb8aa3b, v194
	v_mul_f32_e32 v195, 0x3fb8aa3b, v195
	v_exp_f32_e32 v192, v192
	v_exp_f32_e32 v193, v193
	v_exp_f32_e32 v194, v194
	v_exp_f32_e32 v195, v195
	s_nop 0
	v_mul_f32_e32 v196, v62, v192
	v_mul_f32_e32 v197, v63, v193
	v_mul_f32_e32 v198, v64, v194
	v_mul_f32_e32 v199, v65, v195
	v_lshl_add_u64 v[202:203], v[172:173], 0, v[208:209]
	v_cvt_pk_bf16_f32 v200, v196, v196
	v_cvt_pk_bf16_f32 v201, v198, v197
	v_cvt_pk_bf16_f32 v204, v199, v199
	s_nop 0
	global_store_short v[202:203], v200, off
	global_store_dword v[202:203], v201, off offset:-4
	global_store_short v[202:203], v204, off offset:-6
	v_mul_f32_e64 v192, v188, |v165|
	v_mul_f32_e64 v193, v189, |v165|
	v_mul_f32_e64 v194, v190, |v165|
	v_mul_f32_e64 v195, v191, |v165|
	v_mul_f32_e32 v192, 0x3fb8aa3b, v192
	v_mul_f32_e32 v193, 0x3fb8aa3b, v193
	v_mul_f32_e32 v194, 0x3fb8aa3b, v194
	v_mul_f32_e32 v195, 0x3fb8aa3b, v195
	v_exp_f32_e32 v192, v192
	v_exp_f32_e32 v193, v193
	v_exp_f32_e32 v194, v194
	v_exp_f32_e32 v195, v195
	s_nop 0
	v_mul_f32_e32 v196, v58, v192
	v_mul_f32_e32 v197, v59, v193
	v_mul_f32_e32 v198, v60, v194
	v_mul_f32_e32 v199, v61, v195
	v_lshl_add_u64 v[202:203], v[174:175], 0, v[208:209]
	v_cvt_pk_bf16_f32 v200, v196, v196
	v_cvt_pk_bf16_f32 v201, v198, v197
	v_cvt_pk_bf16_f32 v204, v199, v199
	s_nop 0
	global_store_short v[202:203], v200, off
	global_store_dword v[202:203], v201, off offset:-4
	global_store_short v[202:203], v204, off offset:-6
	v_mul_f32_e64 v192, v188, |v166|
	v_mul_f32_e64 v193, v189, |v166|
	v_mul_f32_e64 v194, v190, |v166|
	v_mul_f32_e64 v195, v191, |v166|
	v_mul_f32_e32 v192, 0x3fb8aa3b, v192
	v_mul_f32_e32 v193, 0x3fb8aa3b, v193
	v_mul_f32_e32 v194, 0x3fb8aa3b, v194
	v_mul_f32_e32 v195, 0x3fb8aa3b, v195
	v_exp_f32_e32 v192, v192
	v_exp_f32_e32 v193, v193
	v_exp_f32_e32 v194, v194
	v_exp_f32_e32 v195, v195
; __device__ __forceinline__ bf16_t f2bf(float f) { return (bf16_t)(pack2(f, f) & 0xffffu); }
;   __device__ __forceinline__ void r4(int g, int rig, int col, f32x4 v) const {
;     const int c = col & 1023; const bool bwd = col >= 1024;
;     const float dec = fabsf(decay[c]);
;     bf16_t* rp = Rf + (size_t)c * 4096;
; #pragma unroll
;     for (int j = 0; j < 4; ++j) {
;       const int t = rig + j;
;       const float val = v[j] * __expf(-(float)t * (1.0f / 2047.0f) * dec);
;       if (!bwd) rp[2048 - t] = f2bf(val);
;       else if (t > 0) rp[2048 + t] = f2bf(val);
;       else rp[0] = 0;
;     }
;   }
	s_nop 0
	v_mul_f32_e32 v196, v54, v192
	v_mul_f32_e32 v197, v55, v193
	v_mul_f32_e32 v198, v56, v194
	v_mul_f32_e32 v199, v57, v195
	v_lshl_add_u64 v[202:203], v[176:177], 0, v[208:209]
	v_cvt_pk_bf16_f32 v200, v196, v196
	v_cvt_pk_bf16_f32 v201, v198, v197
	v_cvt_pk_bf16_f32 v204, v199, v199
	s_nop 0
	global_store_short v[202:203], v200, off
	global_store_dword v[202:203], v201, off offset:-4
	global_store_short v[202:203], v204, off offset:-6
	v_mul_f32_e64 v192, v188, |v167|
	v_mul_f32_e64 v193, v189, |v167|
	v_mul_f32_e64 v194, v190, |v167|
	v_mul_f32_e64 v195, v191, |v167|
	v_mul_f32_e32 v192, 0x3fb8aa3b, v192
	v_mul_f32_e32 v193, 0x3fb8aa3b, v193
	v_mul_f32_e32 v194, 0x3fb8aa3b, v194
	v_mul_f32_e32 v195, 0x3fb8aa3b, v195
	v_exp_f32_e32 v192, v192
	v_exp_f32_e32 v193, v193
	v_exp_f32_e32 v194, v194
	v_exp_f32_e32 v195, v195
	s_nop 0
	v_mul_f32_e32 v196, v50, v192
	v_mul_f32_e32 v197, v51, v193
	v_mul_f32_e32 v198, v52, v194
	v_mul_f32_e32 v199, v53, v195
	v_lshl_add_u64 v[202:203], v[178:179], 0, v[208:209]
	v_cvt_pk_bf16_f32 v200, v196, v196
	v_cvt_pk_bf16_f32 v201, v198, v197
	v_cvt_pk_bf16_f32 v204, v199, v199
	s_nop 0
	global_store_short v[202:203], v200, off
	global_store_dword v[202:203], v201, off offset:-4
	global_store_short v[202:203], v204, off offset:-6
	v_mul_f32_e64 v192, v188, |v168|
	v_mul_f32_e64 v193, v189, |v168|
	v_mul_f32_e64 v194, v190, |v168|
	v_mul_f32_e64 v195, v191, |v168|
	v_mul_f32_e32 v192, 0x3fb8aa3b, v192
	v_mul_f32_e32 v193, 0x3fb8aa3b, v193
	v_mul_f32_e32 v194, 0x3fb8aa3b, v194
	v_mul_f32_e32 v195, 0x3fb8aa3b, v195
	v_exp_f32_e32 v192, v192
	v_exp_f32_e32 v193, v193
	v_exp_f32_e32 v194, v194
	v_exp_f32_e32 v195, v195
	s_nop 0
	v_mul_f32_e32 v196, v46, v192
	v_mul_f32_e32 v197, v47, v193
	v_mul_f32_e32 v198, v48, v194
	v_mul_f32_e32 v199, v49, v195
	v_lshl_add_u64 v[202:203], v[180:181], 0, v[208:209]
	v_cvt_pk_bf16_f32 v200, v196, v196
	v_cvt_pk_bf16_f32 v201, v198, v197
	v_cvt_pk_bf16_f32 v204, v199, v199
	s_nop 0
	global_store_short v[202:203], v200, off
	global_store_dword v[202:203], v201, off offset:-4
	global_store_short v[202:203], v204, off offset:-6
	v_mul_f32_e64 v192, v188, |v169|
	v_mul_f32_e64 v193, v189, |v169|
	v_mul_f32_e64 v194, v190, |v169|
	v_mul_f32_e64 v195, v191, |v169|
	v_mul_f32_e32 v192, 0x3fb8aa3b, v192
	v_mul_f32_e32 v193, 0x3fb8aa3b, v193
	v_mul_f32_e32 v194, 0x3fb8aa3b, v194
	v_mul_f32_e32 v195, 0x3fb8aa3b, v195
	v_exp_f32_e32 v192, v192
	v_exp_f32_e32 v193, v193
	v_exp_f32_e32 v194, v194
	v_exp_f32_e32 v195, v195
	s_nop 0
	v_mul_f32_e32 v196, v42, v192
	v_mul_f32_e32 v197, v43, v193
	v_mul_f32_e32 v198, v44, v194
	v_mul_f32_e32 v199, v45, v195
	v_lshl_add_u64 v[202:203], v[182:183], 0, v[208:209]
	v_cvt_pk_bf16_f32 v200, v196, v196
	v_cvt_pk_bf16_f32 v201, v198, v197
	v_cvt_pk_bf16_f32 v204, v199, v199
	s_nop 0
	global_store_short v[202:203], v200, off
	global_store_dword v[202:203], v201, off offset:-4
	global_store_short v[202:203], v204, off offset:-6
	v_mul_f32_e64 v192, v188, |v170|
	v_mul_f32_e64 v193, v189, |v170|
	v_mul_f32_e64 v194, v190, |v170|
	v_mul_f32_e64 v195, v191, |v170|
	v_mul_f32_e32 v192, 0x3fb8aa3b, v192
	v_mul_f32_e32 v193, 0x3fb8aa3b, v193
	v_mul_f32_e32 v194, 0x3fb8aa3b, v194
	v_mul_f32_e32 v195, 0x3fb8aa3b, v195
	v_exp_f32_e32 v192, v192
	v_exp_f32_e32 v193, v193
	v_exp_f32_e32 v194, v194
	v_exp_f32_e32 v195, v195
	s_nop 0
	v_mul_f32_e32 v196, v38, v192
	v_mul_f32_e32 v197, v39, v193
	v_mul_f32_e32 v198, v40, v194
	v_mul_f32_e32 v199, v41, v195
	v_lshl_add_u64 v[202:203], v[184:185], 0, v[208:209]
	v_cvt_pk_bf16_f32 v200, v196, v196
	v_cvt_pk_bf16_f32 v201, v198, v197
	v_cvt_pk_bf16_f32 v204, v199, v199
	s_nop 0
	global_store_short v[202:203], v200, off
	global_store_dword v[202:203], v201, off offset:-4
	global_store_short v[202:203], v204, off offset:-6
	v_mul_f32_e64 v192, v188, |v171|
	v_mul_f32_e64 v193, v189, |v171|
	v_mul_f32_e64 v194, v190, |v171|
	v_mul_f32_e64 v195, v191, |v171|
	v_mul_f32_e32 v192, 0x3fb8aa3b, v192
	v_mul_f32_e32 v193, 0x3fb8aa3b, v193
	v_mul_f32_e32 v194, 0x3fb8aa3b, v194
	v_mul_f32_e32 v195, 0x3fb8aa3b, v195
	v_exp_f32_e32 v192, v192
	v_exp_f32_e32 v193, v193
	v_exp_f32_e32 v194, v194
	v_exp_f32_e32 v195, v195
	s_nop 0
	v_mul_f32_e32 v196, v34, v192
	v_mul_f32_e32 v197, v35, v193
	v_mul_f32_e32 v198, v36, v194
	v_mul_f32_e32 v199, v37, v195
	v_lshl_add_u64 v[202:203], v[186:187], 0, v[208:209]
	v_cvt_pk_bf16_f32 v200, v196, v196
	v_cvt_pk_bf16_f32 v201, v198, v197
	v_cvt_pk_bf16_f32 v204, v199, v199
	s_nop 0
	global_store_short v[202:203], v200, off
	global_store_dword v[202:203], v201, off offset:-4
	global_store_short v[202:203], v204, off offset:-6
	v_or_b32_e32 v206, 48, v130
	v_cvt_f32_i32_e32 v188, v206
	v_or_b32_e32 v204, 1, v206
	v_cvt_f32_i32_e32 v189, v204
	v_or_b32_e32 v204, 2, v206
	v_cvt_f32_i32_e32 v190, v204
	v_or_b32_e32 v204, 3, v206
	v_cvt_f32_i32_e32 v191, v204
	v_mul_f32_e32 v188, 0xba001002, v188
	v_mul_f32_e32 v189, 0xba001002, v189
	v_mul_f32_e32 v190, 0xba001002, v190
	v_mul_f32_e32 v191, 0xba001002, v191
	v_sub_u32_e32 v208, 0x800, v206
	v_lshlrev_b32_e32 v208, 1, v208
	v_mul_f32_e64 v192, v188, |v164|
	v_mul_f32_e64 v193, v189, |v164|
	v_mul_f32_e64 v194, v190, |v164|
	v_mul_f32_e64 v195, v191, |v164|
	v_mul_f32_e32 v192, 0x3fb8aa3b, v192
	v_mul_f32_e32 v193, 0x3fb8aa3b, v193
	v_mul_f32_e32 v194, 0x3fb8aa3b, v194
	v_mul_f32_e32 v195, 0x3fb8aa3b, v195
	v_exp_f32_e32 v192, v192
	v_exp_f32_e32 v193, v193
	v_exp_f32_e32 v194, v194
	v_exp_f32_e32 v195, v195
	s_nop 0
	v_mul_f32_e32 v196, v30, v192
	v_mul_f32_e32 v197, v31, v193
	v_mul_f32_e32 v198, v32, v194
	v_mul_f32_e32 v199, v33, v195
; __device__ __forceinline__ bf16_t f2bf(float f) { return (bf16_t)(pack2(f, f) & 0xffffu); }
;   __device__ __forceinline__ void r4(int g, int rig, int col, f32x4 v) const {
;     const int c = col & 1023; const bool bwd = col >= 1024;
;     const float dec = fabsf(decay[c]);
;     bf16_t* rp = Rf + (size_t)c * 4096;
; #pragma unroll
;     for (int j = 0; j < 4; ++j) {
;       const int t = rig + j;
;       const float val = v[j] * __expf(-(float)t * (1.0f / 2047.0f) * dec);
;       if (!bwd) rp[2048 - t] = f2bf(val);
;       else if (t > 0) rp[2048 + t] = f2bf(val);
;       else rp[0] = 0;
;     }
;   }
	v_lshl_add_u64 v[202:203], v[172:173], 0, v[208:209]
	v_cvt_pk_bf16_f32 v200, v196, v196
	v_cvt_pk_bf16_f32 v201, v198, v197
	v_cvt_pk_bf16_f32 v204, v199, v199
	s_nop 0
	global_store_short v[202:203], v200, off
	global_store_dword v[202:203], v201, off offset:-4
	global_store_short v[202:203], v204, off offset:-6
	v_mul_f32_e64 v192, v188, |v165|
	v_mul_f32_e64 v193, v189, |v165|
	v_mul_f32_e64 v194, v190, |v165|
	v_mul_f32_e64 v195, v191, |v165|
	v_mul_f32_e32 v192, 0x3fb8aa3b, v192
	v_mul_f32_e32 v193, 0x3fb8aa3b, v193
	v_mul_f32_e32 v194, 0x3fb8aa3b, v194
	v_mul_f32_e32 v195, 0x3fb8aa3b, v195
	v_exp_f32_e32 v192, v192
	v_exp_f32_e32 v193, v193
	v_exp_f32_e32 v194, v194
	v_exp_f32_e32 v195, v195
	s_nop 0
	v_mul_f32_e32 v196, v26, v192
	v_mul_f32_e32 v197, v27, v193
	v_mul_f32_e32 v198, v28, v194
	v_mul_f32_e32 v199, v29, v195
	v_lshl_add_u64 v[202:203], v[174:175], 0, v[208:209]
	v_cvt_pk_bf16_f32 v200, v196, v196
	v_cvt_pk_bf16_f32 v201, v198, v197
	v_cvt_pk_bf16_f32 v204, v199, v199
	s_nop 0
	global_store_short v[202:203], v200, off
	global_store_dword v[202:203], v201, off offset:-4
	global_store_short v[202:203], v204, off offset:-6
	v_mul_f32_e64 v192, v188, |v166|
	v_mul_f32_e64 v193, v189, |v166|
	v_mul_f32_e64 v194, v190, |v166|
	v_mul_f32_e64 v195, v191, |v166|
	v_mul_f32_e32 v192, 0x3fb8aa3b, v192
	v_mul_f32_e32 v193, 0x3fb8aa3b, v193
	v_mul_f32_e32 v194, 0x3fb8aa3b, v194
	v_mul_f32_e32 v195, 0x3fb8aa3b, v195
	v_exp_f32_e32 v192, v192
	v_exp_f32_e32 v193, v193
	v_exp_f32_e32 v194, v194
	v_exp_f32_e32 v195, v195
	s_nop 0
	v_mul_f32_e32 v196, v22, v192
	v_mul_f32_e32 v197, v23, v193
	v_mul_f32_e32 v198, v24, v194
	v_mul_f32_e32 v199, v25, v195
	v_lshl_add_u64 v[202:203], v[176:177], 0, v[208:209]
	v_cvt_pk_bf16_f32 v200, v196, v196
	v_cvt_pk_bf16_f32 v201, v198, v197
	v_cvt_pk_bf16_f32 v204, v199, v199
	s_nop 0
	global_store_short v[202:203], v200, off
	global_store_dword v[202:203], v201, off offset:-4
	global_store_short v[202:203], v204, off offset:-6
	v_mul_f32_e64 v192, v188, |v167|
	v_mul_f32_e64 v193, v189, |v167|
	v_mul_f32_e64 v194, v190, |v167|
	v_mul_f32_e64 v195, v191, |v167|
	v_mul_f32_e32 v192, 0x3fb8aa3b, v192
	v_mul_f32_e32 v193, 0x3fb8aa3b, v193
	v_mul_f32_e32 v194, 0x3fb8aa3b, v194
	v_mul_f32_e32 v195, 0x3fb8aa3b, v195
	v_exp_f32_e32 v192, v192
	v_exp_f32_e32 v193, v193
	v_exp_f32_e32 v194, v194
	v_exp_f32_e32 v195, v195
	s_nop 0
	v_mul_f32_e32 v196, v18, v192
	v_mul_f32_e32 v197, v19, v193
	v_mul_f32_e32 v198, v20, v194
	v_mul_f32_e32 v199, v21, v195
	v_lshl_add_u64 v[202:203], v[178:179], 0, v[208:209]
	v_cvt_pk_bf16_f32 v200, v196, v196
	v_cvt_pk_bf16_f32 v201, v198, v197
	v_cvt_pk_bf16_f32 v204, v199, v199
	s_nop 0
	global_store_short v[202:203], v200, off
	global_store_dword v[202:203], v201, off offset:-4
	global_store_short v[202:203], v204, off offset:-6
	v_mul_f32_e64 v192, v188, |v168|
	v_mul_f32_e64 v193, v189, |v168|
	v_mul_f32_e64 v194, v190, |v168|
	v_mul_f32_e64 v195, v191, |v168|
	v_mul_f32_e32 v192, 0x3fb8aa3b, v192
	v_mul_f32_e32 v193, 0x3fb8aa3b, v193
	v_mul_f32_e32 v194, 0x3fb8aa3b, v194
	v_mul_f32_e32 v195, 0x3fb8aa3b, v195
	v_exp_f32_e32 v192, v192
	v_exp_f32_e32 v193, v193
	v_exp_f32_e32 v194, v194
	v_exp_f32_e32 v195, v195
	s_nop 0
	v_mul_f32_e32 v196, v14, v192
	v_mul_f32_e32 v197, v15, v193
	v_mul_f32_e32 v198, v16, v194
	v_mul_f32_e32 v199, v17, v195
	v_lshl_add_u64 v[202:203], v[180:181], 0, v[208:209]
	v_cvt_pk_bf16_f32 v200, v196, v196
	v_cvt_pk_bf16_f32 v201, v198, v197
	v_cvt_pk_bf16_f32 v204, v199, v199
	s_nop 0
	global_store_short v[202:203], v200, off
	global_store_dword v[202:203], v201, off offset:-4
	global_store_short v[202:203], v204, off offset:-6
	v_mul_f32_e64 v192, v188, |v169|
	v_mul_f32_e64 v193, v189, |v169|
	v_mul_f32_e64 v194, v190, |v169|
	v_mul_f32_e64 v195, v191, |v169|
	v_mul_f32_e32 v192, 0x3fb8aa3b, v192
	v_mul_f32_e32 v193, 0x3fb8aa3b, v193
	v_mul_f32_e32 v194, 0x3fb8aa3b, v194
	v_mul_f32_e32 v195, 0x3fb8aa3b, v195
	v_exp_f32_e32 v192, v192
	v_exp_f32_e32 v193, v193
	v_exp_f32_e32 v194, v194
	v_exp_f32_e32 v195, v195
	s_nop 0
	v_mul_f32_e32 v196, v10, v192
	v_mul_f32_e32 v197, v11, v193
	v_mul_f32_e32 v198, v12, v194
	v_mul_f32_e32 v199, v13, v195
	v_lshl_add_u64 v[202:203], v[182:183], 0, v[208:209]
	v_cvt_pk_bf16_f32 v200, v196, v196
	v_cvt_pk_bf16_f32 v201, v198, v197
	v_cvt_pk_bf16_f32 v204, v199, v199
	s_nop 0
	global_store_short v[202:203], v200, off
	global_store_dword v[202:203], v201, off offset:-4
	global_store_short v[202:203], v204, off offset:-6
	v_mul_f32_e64 v192, v188, |v170|
	v_mul_f32_e64 v193, v189, |v170|
	v_mul_f32_e64 v194, v190, |v170|
	v_mul_f32_e64 v195, v191, |v170|
	v_mul_f32_e32 v192, 0x3fb8aa3b, v192
	v_mul_f32_e32 v193, 0x3fb8aa3b, v193
	v_mul_f32_e32 v194, 0x3fb8aa3b, v194
	v_mul_f32_e32 v195, 0x3fb8aa3b, v195
	v_exp_f32_e32 v192, v192
	v_exp_f32_e32 v193, v193
	v_exp_f32_e32 v194, v194
	v_exp_f32_e32 v195, v195
	s_nop 0
	v_mul_f32_e32 v196, v6, v192
	v_mul_f32_e32 v197, v7, v193
	v_mul_f32_e32 v198, v8, v194
	v_mul_f32_e32 v199, v9, v195
	v_lshl_add_u64 v[202:203], v[184:185], 0, v[208:209]
	v_cvt_pk_bf16_f32 v200, v196, v196
	v_cvt_pk_bf16_f32 v201, v198, v197
	v_cvt_pk_bf16_f32 v204, v199, v199
	s_nop 0
	global_store_short v[202:203], v200, off
	global_store_dword v[202:203], v201, off offset:-4
	global_store_short v[202:203], v204, off offset:-6
	v_mul_f32_e64 v192, v188, |v171|
	v_mul_f32_e64 v193, v189, |v171|
	v_mul_f32_e64 v194, v190, |v171|
	v_mul_f32_e64 v195, v191, |v171|
	v_mul_f32_e32 v192, 0x3fb8aa3b, v192
	v_mul_f32_e32 v193, 0x3fb8aa3b, v193
	v_mul_f32_e32 v194, 0x3fb8aa3b, v194
	v_mul_f32_e32 v195, 0x3fb8aa3b, v195
	v_exp_f32_e32 v192, v192
	v_exp_f32_e32 v193, v193
	v_exp_f32_e32 v194, v194
	v_exp_f32_e32 v195, v195
	s_nop 0
	v_mul_f32_e32 v196, v2, v192
	v_mul_f32_e32 v197, v3, v193
	v_mul_f32_e32 v198, v4, v194
	v_mul_f32_e32 v199, v5, v195
	v_lshl_add_u64 v[202:203], v[186:187], 0, v[208:209]
	v_cvt_pk_bf16_f32 v200, v196, v196
	v_cvt_pk_bf16_f32 v201, v198, v197
	v_cvt_pk_bf16_f32 v204, v199, v199
	s_nop 0
	global_store_short v[202:203], v200, off
	global_store_dword v[202:203], v201, off offset:-4
	global_store_short v[202:203], v204, off offset:-6
	s_branch .Lfilt_done
; __device__ __forceinline__ bf16_t f2bf(float f) { return (bf16_t)(pack2(f, f) & 0xffffu); }
;   __device__ __forceinline__ void r4(int g, int rig, int col, f32x4 v) const {
;     const int c = col & 1023; const bool bwd = col >= 1024;
;     const float dec = fabsf(decay[c]);
;     bf16_t* rp = Rf + (size_t)c * 4096;
; #pragma unroll
;     for (int j = 0; j < 4; ++j) {
;       const int t = rig + j;
;       const float val = v[j] * __expf(-(float)t * (1.0f / 2047.0f) * dec);
;       if (!bwd) rp[2048 - t] = f2bf(val);
;       else if (t > 0) rp[2048 + t] = f2bf(val);
;       else rp[0] = 0;
;     }
;   }
.Lfilt_bwd:
	v_mov_b32_e32 v206, v130
	v_cvt_f32_i32_e32 v188, v206
	v_or_b32_e32 v204, 1, v206
	v_cvt_f32_i32_e32 v189, v204
	v_or_b32_e32 v204, 2, v206
	v_cvt_f32_i32_e32 v190, v204
	v_or_b32_e32 v204, 3, v206
	v_cvt_f32_i32_e32 v191, v204
	v_mul_f32_e32 v188, 0xba001002, v188
	v_mul_f32_e32 v189, 0xba001002, v189
	v_mul_f32_e32 v190, 0xba001002, v190
	v_mul_f32_e32 v191, 0xba001002, v191
	v_lshlrev_b32_e32 v208, 1, v206
	v_add_u32_e32 v208, 0x1000, v208
	v_mul_f32_e64 v192, v188, |v164|
	v_mul_f32_e64 v193, v189, |v164|
	v_mul_f32_e64 v194, v190, |v164|
	v_mul_f32_e64 v195, v191, |v164|
	v_mul_f32_e32 v192, 0x3fb8aa3b, v192
	v_mul_f32_e32 v193, 0x3fb8aa3b, v193
	v_mul_f32_e32 v194, 0x3fb8aa3b, v194
	v_mul_f32_e32 v195, 0x3fb8aa3b, v195
	v_exp_f32_e32 v192, v192
	v_exp_f32_e32 v193, v193
	v_exp_f32_e32 v194, v194
	v_exp_f32_e32 v195, v195
	s_nop 0
	v_mul_f32_e32 v196, v126, v192
	v_mul_f32_e32 v197, v127, v193
	v_mul_f32_e32 v198, v128, v194
	v_mul_f32_e32 v199, v129, v195
	v_lshl_add_u64 v[202:203], v[172:173], 0, v[208:209]
	v_cvt_pk_bf16_f32 v200, v196, v197
	v_cvt_pk_bf16_f32 v201, v198, v199
	v_lshrrev_b32_e32 v204, 16, v200
	s_mov_b64 s[14:15], exec
	s_andn2_b64 exec, exec, s[12:13]
	global_store_dwordx2 v[202:203], v[200:201], off
	s_and_b64 exec, s[14:15], s[12:13]
	global_store_short v[172:173], v131, off
	global_store_short v[202:203], v204, off offset:2
	global_store_dword v[202:203], v201, off offset:4
	s_mov_b64 exec, s[14:15]
	v_mul_f32_e64 v192, v188, |v165|
	v_mul_f32_e64 v193, v189, |v165|
	v_mul_f32_e64 v194, v190, |v165|
	v_mul_f32_e64 v195, v191, |v165|
	v_mul_f32_e32 v192, 0x3fb8aa3b, v192
	v_mul_f32_e32 v193, 0x3fb8aa3b, v193
	v_mul_f32_e32 v194, 0x3fb8aa3b, v194
	v_mul_f32_e32 v195, 0x3fb8aa3b, v195
	v_exp_f32_e32 v192, v192
	v_exp_f32_e32 v193, v193
	v_exp_f32_e32 v194, v194
	v_exp_f32_e32 v195, v195
	s_nop 0
	v_mul_f32_e32 v196, v122, v192
	v_mul_f32_e32 v197, v123, v193
	v_mul_f32_e32 v198, v124, v194
	v_mul_f32_e32 v199, v125, v195
	v_lshl_add_u64 v[202:203], v[174:175], 0, v[208:209]
	v_cvt_pk_bf16_f32 v200, v196, v197
	v_cvt_pk_bf16_f32 v201, v198, v199
	v_lshrrev_b32_e32 v204, 16, v200
	s_mov_b64 s[14:15], exec
	s_andn2_b64 exec, exec, s[12:13]
	global_store_dwordx2 v[202:203], v[200:201], off
	s_and_b64 exec, s[14:15], s[12:13]
	global_store_short v[174:175], v131, off
	global_store_short v[202:203], v204, off offset:2
	global_store_dword v[202:203], v201, off offset:4
	s_mov_b64 exec, s[14:15]
	v_mul_f32_e64 v192, v188, |v166|
	v_mul_f32_e64 v193, v189, |v166|
	v_mul_f32_e64 v194, v190, |v166|
	v_mul_f32_e64 v195, v191, |v166|
	v_mul_f32_e32 v192, 0x3fb8aa3b, v192
	v_mul_f32_e32 v193, 0x3fb8aa3b, v193
	v_mul_f32_e32 v194, 0x3fb8aa3b, v194
	v_mul_f32_e32 v195, 0x3fb8aa3b, v195
	v_exp_f32_e32 v192, v192
	v_exp_f32_e32 v193, v193
	v_exp_f32_e32 v194, v194
	v_exp_f32_e32 v195, v195
	s_nop 0
	v_mul_f32_e32 v196, v118, v192
	v_mul_f32_e32 v197, v119, v193
	v_mul_f32_e32 v198, v120, v194
	v_mul_f32_e32 v199, v121, v195
	v_lshl_add_u64 v[202:203], v[176:177], 0, v[208:209]
	v_cvt_pk_bf16_f32 v200, v196, v197
	v_cvt_pk_bf16_f32 v201, v198, v199
	v_lshrrev_b32_e32 v204, 16, v200
	s_mov_b64 s[14:15], exec
	s_andn2_b64 exec, exec, s[12:13]
	global_store_dwordx2 v[202:203], v[200:201], off
	s_and_b64 exec, s[14:15], s[12:13]
	global_store_short v[176:177], v131, off
	global_store_short v[202:203], v204, off offset:2
	global_store_dword v[202:203], v201, off offset:4
	s_mov_b64 exec, s[14:15]
	v_mul_f32_e64 v192, v188, |v167|
	v_mul_f32_e64 v193, v189, |v167|
	v_mul_f32_e64 v194, v190, |v167|
	v_mul_f32_e64 v195, v191, |v167|
	v_mul_f32_e32 v192, 0x3fb8aa3b, v192
	v_mul_f32_e32 v193, 0x3fb8aa3b, v193
	v_mul_f32_e32 v194, 0x3fb8aa3b, v194
	v_mul_f32_e32 v195, 0x3fb8aa3b, v195
	v_exp_f32_e32 v192, v192
	v_exp_f32_e32 v193, v193
	v_exp_f32_e32 v194, v194
	v_exp_f32_e32 v195, v195
	s_nop 0
	v_mul_f32_e32 v196, v114, v192
	v_mul_f32_e32 v197, v115, v193
	v_mul_f32_e32 v198, v116, v194
	v_mul_f32_e32 v199, v117, v195
	v_lshl_add_u64 v[202:203], v[178:179], 0, v[208:209]
	v_cvt_pk_bf16_f32 v200, v196, v197
	v_cvt_pk_bf16_f32 v201, v198, v199
	v_lshrrev_b32_e32 v204, 16, v200
	s_mov_b64 s[14:15], exec
	s_andn2_b64 exec, exec, s[12:13]
	global_store_dwordx2 v[202:203], v[200:201], off
	s_and_b64 exec, s[14:15], s[12:13]
	global_store_short v[178:179], v131, off
	global_store_short v[202:203], v204, off offset:2
	global_store_dword v[202:203], v201, off offset:4
	s_mov_b64 exec, s[14:15]
	v_mul_f32_e64 v192, v188, |v168|
	v_mul_f32_e64 v193, v189, |v168|
	v_mul_f32_e64 v194, v190, |v168|
	v_mul_f32_e64 v195, v191, |v168|
	v_mul_f32_e32 v192, 0x3fb8aa3b, v192
	v_mul_f32_e32 v193, 0x3fb8aa3b, v193
	v_mul_f32_e32 v194, 0x3fb8aa3b, v194
	v_mul_f32_e32 v195, 0x3fb8aa3b, v195
	v_exp_f32_e32 v192, v192
	v_exp_f32_e32 v193, v193
	v_exp_f32_e32 v194, v194
	v_exp_f32_e32 v195, v195
	s_nop 0
	v_mul_f32_e32 v196, v110, v192
	v_mul_f32_e32 v197, v111, v193
	v_mul_f32_e32 v198, v112, v194
	v_mul_f32_e32 v199, v113, v195
	v_lshl_add_u64 v[202:203], v[180:181], 0, v[208:209]
	v_cvt_pk_bf16_f32 v200, v196, v197
	v_cvt_pk_bf16_f32 v201, v198, v199
	v_lshrrev_b32_e32 v204, 16, v200
	s_mov_b64 s[14:15], exec
	s_andn2_b64 exec, exec, s[12:13]
	global_store_dwordx2 v[202:203], v[200:201], off
	s_and_b64 exec, s[14:15], s[12:13]
	global_store_short v[180:181], v131, off
	global_store_short v[202:203], v204, off offset:2
	global_store_dword v[202:203], v201, off offset:4
	s_mov_b64 exec, s[14:15]
	v_mul_f32_e64 v192, v188, |v169|
	v_mul_f32_e64 v193, v189, |v169|
	v_mul_f32_e64 v194, v190, |v169|
	v_mul_f32_e64 v195, v191, |v169|
; __device__ __forceinline__ bf16_t f2bf(float f) { return (bf16_t)(pack2(f, f) & 0xffffu); }
;   __device__ __forceinline__ void r4(int g, int rig, int col, f32x4 v) const {
;     const int c = col & 1023; const bool bwd = col >= 1024;
;     const float dec = fabsf(decay[c]);
;     bf16_t* rp = Rf + (size_t)c * 4096;
; #pragma unroll
;     for (int j = 0; j < 4; ++j) {
;       const int t = rig + j;
;       const float val = v[j] * __expf(-(float)t * (1.0f / 2047.0f) * dec);
;       if (!bwd) rp[2048 - t] = f2bf(val);
;       else if (t > 0) rp[2048 + t] = f2bf(val);
;       else rp[0] = 0;
;     }
;   }
	v_mul_f32_e32 v192, 0x3fb8aa3b, v192
	v_mul_f32_e32 v193, 0x3fb8aa3b, v193
	v_mul_f32_e32 v194, 0x3fb8aa3b, v194
	v_mul_f32_e32 v195, 0x3fb8aa3b, v195
	v_exp_f32_e32 v192, v192
	v_exp_f32_e32 v193, v193
	v_exp_f32_e32 v194, v194
	v_exp_f32_e32 v195, v195
	s_nop 0
	v_mul_f32_e32 v196, v106, v192
	v_mul_f32_e32 v197, v107, v193
	v_mul_f32_e32 v198, v108, v194
	v_mul_f32_e32 v199, v109, v195
	v_lshl_add_u64 v[202:203], v[182:183], 0, v[208:209]
	v_cvt_pk_bf16_f32 v200, v196, v197
	v_cvt_pk_bf16_f32 v201, v198, v199
	v_lshrrev_b32_e32 v204, 16, v200
	s_mov_b64 s[14:15], exec
	s_andn2_b64 exec, exec, s[12:13]
	global_store_dwordx2 v[202:203], v[200:201], off
	s_and_b64 exec, s[14:15], s[12:13]
	global_store_short v[182:183], v131, off
	global_store_short v[202:203], v204, off offset:2
	global_store_dword v[202:203], v201, off offset:4
	s_mov_b64 exec, s[14:15]
	v_mul_f32_e64 v192, v188, |v170|
	v_mul_f32_e64 v193, v189, |v170|
	v_mul_f32_e64 v194, v190, |v170|
	v_mul_f32_e64 v195, v191, |v170|
	v_mul_f32_e32 v192, 0x3fb8aa3b, v192
	v_mul_f32_e32 v193, 0x3fb8aa3b, v193
	v_mul_f32_e32 v194, 0x3fb8aa3b, v194
	v_mul_f32_e32 v195, 0x3fb8aa3b, v195
	v_exp_f32_e32 v192, v192
	v_exp_f32_e32 v193, v193
	v_exp_f32_e32 v194, v194
	v_exp_f32_e32 v195, v195
	s_nop 0
	v_mul_f32_e32 v196, v102, v192
	v_mul_f32_e32 v197, v103, v193
	v_mul_f32_e32 v198, v104, v194
	v_mul_f32_e32 v199, v105, v195
	v_lshl_add_u64 v[202:203], v[184:185], 0, v[208:209]
	v_cvt_pk_bf16_f32 v200, v196, v197
	v_cvt_pk_bf16_f32 v201, v198, v199
	v_lshrrev_b32_e32 v204, 16, v200
	s_mov_b64 s[14:15], exec
	s_andn2_b64 exec, exec, s[12:13]
	global_store_dwordx2 v[202:203], v[200:201], off
	s_and_b64 exec, s[14:15], s[12:13]
	global_store_short v[184:185], v131, off
	global_store_short v[202:203], v204, off offset:2
	global_store_dword v[202:203], v201, off offset:4
	s_mov_b64 exec, s[14:15]
	v_mul_f32_e64 v192, v188, |v171|
	v_mul_f32_e64 v193, v189, |v171|
	v_mul_f32_e64 v194, v190, |v171|
	v_mul_f32_e64 v195, v191, |v171|
	v_mul_f32_e32 v192, 0x3fb8aa3b, v192
	v_mul_f32_e32 v193, 0x3fb8aa3b, v193
	v_mul_f32_e32 v194, 0x3fb8aa3b, v194
	v_mul_f32_e32 v195, 0x3fb8aa3b, v195
	v_exp_f32_e32 v192, v192
	v_exp_f32_e32 v193, v193
	v_exp_f32_e32 v194, v194
	v_exp_f32_e32 v195, v195
	s_nop 0
	v_mul_f32_e32 v196, v98, v192
	v_mul_f32_e32 v197, v99, v193
	v_mul_f32_e32 v198, v100, v194
	v_mul_f32_e32 v199, v101, v195
	v_lshl_add_u64 v[202:203], v[186:187], 0, v[208:209]
	v_cvt_pk_bf16_f32 v200, v196, v197
	v_cvt_pk_bf16_f32 v201, v198, v199
	v_lshrrev_b32_e32 v204, 16, v200
	s_mov_b64 s[14:15], exec
	s_andn2_b64 exec, exec, s[12:13]
	global_store_dwordx2 v[202:203], v[200:201], off
	s_and_b64 exec, s[14:15], s[12:13]
	global_store_short v[186:187], v131, off
	global_store_short v[202:203], v204, off offset:2
	global_store_dword v[202:203], v201, off offset:4
	s_mov_b64 exec, s[14:15]
	v_or_b32_e32 v206, 16, v130
	v_cvt_f32_i32_e32 v188, v206
	v_or_b32_e32 v204, 1, v206
	v_cvt_f32_i32_e32 v189, v204
	v_or_b32_e32 v204, 2, v206
	v_cvt_f32_i32_e32 v190, v204
	v_or_b32_e32 v204, 3, v206
	v_cvt_f32_i32_e32 v191, v204
	v_mul_f32_e32 v188, 0xba001002, v188
	v_mul_f32_e32 v189, 0xba001002, v189
	v_mul_f32_e32 v190, 0xba001002, v190
	v_mul_f32_e32 v191, 0xba001002, v191
	v_lshlrev_b32_e32 v208, 1, v206
	v_add_u32_e32 v208, 0x1000, v208
	v_mul_f32_e64 v192, v188, |v164|
	v_mul_f32_e64 v193, v189, |v164|
	v_mul_f32_e64 v194, v190, |v164|
	v_mul_f32_e64 v195, v191, |v164|
	v_mul_f32_e32 v192, 0x3fb8aa3b, v192
	v_mul_f32_e32 v193, 0x3fb8aa3b, v193
	v_mul_f32_e32 v194, 0x3fb8aa3b, v194
	v_mul_f32_e32 v195, 0x3fb8aa3b, v195
	v_exp_f32_e32 v192, v192
	v_exp_f32_e32 v193, v193
	v_exp_f32_e32 v194, v194
	v_exp_f32_e32 v195, v195
	s_nop 0
	v_mul_f32_e32 v196, v94, v192
	v_mul_f32_e32 v197, v95, v193
	v_mul_f32_e32 v198, v96, v194
	v_mul_f32_e32 v199, v97, v195
	v_lshl_add_u64 v[202:203], v[172:173], 0, v[208:209]
	v_cvt_pk_bf16_f32 v200, v196, v197
	v_cvt_pk_bf16_f32 v201, v198, v199
	s_nop 0
	global_store_dwordx2 v[202:203], v[200:201], off
	v_mul_f32_e64 v192, v188, |v165|
	v_mul_f32_e64 v193, v189, |v165|
	v_mul_f32_e64 v194, v190, |v165|
	v_mul_f32_e64 v195, v191, |v165|
	v_mul_f32_e32 v192, 0x3fb8aa3b, v192
	v_mul_f32_e32 v193, 0x3fb8aa3b, v193
	v_mul_f32_e32 v194, 0x3fb8aa3b, v194
	v_mul_f32_e32 v195, 0x3fb8aa3b, v195
	v_exp_f32_e32 v192, v192
	v_exp_f32_e32 v193, v193
	v_exp_f32_e32 v194, v194
	v_exp_f32_e32 v195, v195
	s_nop 0
	v_mul_f32_e32 v196, v90, v192
	v_mul_f32_e32 v197, v91, v193
	v_mul_f32_e32 v198, v92, v194
	v_mul_f32_e32 v199, v93, v195
	v_lshl_add_u64 v[202:203], v[174:175], 0, v[208:209]
	v_cvt_pk_bf16_f32 v200, v196, v197
	v_cvt_pk_bf16_f32 v201, v198, v199
	s_nop 0
	global_store_dwordx2 v[202:203], v[200:201], off
	v_mul_f32_e64 v192, v188, |v166|
	v_mul_f32_e64 v193, v189, |v166|
	v_mul_f32_e64 v194, v190, |v166|
	v_mul_f32_e64 v195, v191, |v166|
	v_mul_f32_e32 v192, 0x3fb8aa3b, v192
	v_mul_f32_e32 v193, 0x3fb8aa3b, v193
	v_mul_f32_e32 v194, 0x3fb8aa3b, v194
	v_mul_f32_e32 v195, 0x3fb8aa3b, v195
	v_exp_f32_e32 v192, v192
	v_exp_f32_e32 v193, v193
	v_exp_f32_e32 v194, v194
	v_exp_f32_e32 v195, v195
	s_nop 0
	v_mul_f32_e32 v196, v86, v192
	v_mul_f32_e32 v197, v87, v193
	v_mul_f32_e32 v198, v88, v194
	v_mul_f32_e32 v199, v89, v195
	v_lshl_add_u64 v[202:203], v[176:177], 0, v[208:209]
	v_cvt_pk_bf16_f32 v200, v196, v197
	v_cvt_pk_bf16_f32 v201, v198, v199
	s_nop 0
	global_store_dwordx2 v[202:203], v[200:201], off
	v_mul_f32_e64 v192, v188, |v167|
	v_mul_f32_e64 v193, v189, |v167|
	v_mul_f32_e64 v194, v190, |v167|
	v_mul_f32_e64 v195, v191, |v167|
	v_mul_f32_e32 v192, 0x3fb8aa3b, v192
; __device__ __forceinline__ bf16_t f2bf(float f) { return (bf16_t)(pack2(f, f) & 0xffffu); }
;   __device__ __forceinline__ void r4(int g, int rig, int col, f32x4 v) const {
;     const int c = col & 1023; const bool bwd = col >= 1024;
;     const float dec = fabsf(decay[c]);
;     bf16_t* rp = Rf + (size_t)c * 4096;
; #pragma unroll
;     for (int j = 0; j < 4; ++j) {
;       const int t = rig + j;
;       const float val = v[j] * __expf(-(float)t * (1.0f / 2047.0f) * dec);
;       if (!bwd) rp[2048 - t] = f2bf(val);
;       else if (t > 0) rp[2048 + t] = f2bf(val);
;       else rp[0] = 0;
;     }
;   }
	v_mul_f32_e32 v193, 0x3fb8aa3b, v193
	v_mul_f32_e32 v194, 0x3fb8aa3b, v194
	v_mul_f32_e32 v195, 0x3fb8aa3b, v195
	v_exp_f32_e32 v192, v192
	v_exp_f32_e32 v193, v193
	v_exp_f32_e32 v194, v194
	v_exp_f32_e32 v195, v195
	s_nop 0
	v_mul_f32_e32 v196, v82, v192
	v_mul_f32_e32 v197, v83, v193
	v_mul_f32_e32 v198, v84, v194
	v_mul_f32_e32 v199, v85, v195
	v_lshl_add_u64 v[202:203], v[178:179], 0, v[208:209]
	v_cvt_pk_bf16_f32 v200, v196, v197
	v_cvt_pk_bf16_f32 v201, v198, v199
	s_nop 0
	global_store_dwordx2 v[202:203], v[200:201], off
	v_mul_f32_e64 v192, v188, |v168|
	v_mul_f32_e64 v193, v189, |v168|
	v_mul_f32_e64 v194, v190, |v168|
	v_mul_f32_e64 v195, v191, |v168|
	v_mul_f32_e32 v192, 0x3fb8aa3b, v192
	v_mul_f32_e32 v193, 0x3fb8aa3b, v193
	v_mul_f32_e32 v194, 0x3fb8aa3b, v194
	v_mul_f32_e32 v195, 0x3fb8aa3b, v195
	v_exp_f32_e32 v192, v192
	v_exp_f32_e32 v193, v193
	v_exp_f32_e32 v194, v194
	v_exp_f32_e32 v195, v195
	s_nop 0
	v_mul_f32_e32 v196, v78, v192
	v_mul_f32_e32 v197, v79, v193
	v_mul_f32_e32 v198, v80, v194
	v_mul_f32_e32 v199, v81, v195
	v_lshl_add_u64 v[202:203], v[180:181], 0, v[208:209]
	v_cvt_pk_bf16_f32 v200, v196, v197
	v_cvt_pk_bf16_f32 v201, v198, v199
	s_nop 0
	global_store_dwordx2 v[202:203], v[200:201], off
	v_mul_f32_e64 v192, v188, |v169|
	v_mul_f32_e64 v193, v189, |v169|
	v_mul_f32_e64 v194, v190, |v169|
	v_mul_f32_e64 v195, v191, |v169|
	v_mul_f32_e32 v192, 0x3fb8aa3b, v192
	v_mul_f32_e32 v193, 0x3fb8aa3b, v193
	v_mul_f32_e32 v194, 0x3fb8aa3b, v194
	v_mul_f32_e32 v195, 0x3fb8aa3b, v195
	v_exp_f32_e32 v192, v192
	v_exp_f32_e32 v193, v193
	v_exp_f32_e32 v194, v194
	v_exp_f32_e32 v195, v195
	s_nop 0
	v_mul_f32_e32 v196, v74, v192
	v_mul_f32_e32 v197, v75, v193
	v_mul_f32_e32 v198, v76, v194
	v_mul_f32_e32 v199, v77, v195
	v_lshl_add_u64 v[202:203], v[182:183], 0, v[208:209]
	v_cvt_pk_bf16_f32 v200, v196, v197
	v_cvt_pk_bf16_f32 v201, v198, v199
	s_nop 0
	global_store_dwordx2 v[202:203], v[200:201], off
	v_mul_f32_e64 v192, v188, |v170|
	v_mul_f32_e64 v193, v189, |v170|
	v_mul_f32_e64 v194, v190, |v170|
	v_mul_f32_e64 v195, v191, |v170|
	v_mul_f32_e32 v192, 0x3fb8aa3b, v192
	v_mul_f32_e32 v193, 0x3fb8aa3b, v193
	v_mul_f32_e32 v194, 0x3fb8aa3b, v194
	v_mul_f32_e32 v195, 0x3fb8aa3b, v195
	v_exp_f32_e32 v192, v192
	v_exp_f32_e32 v193, v193
	v_exp_f32_e32 v194, v194
	v_exp_f32_e32 v195, v195
	s_nop 0
	v_mul_f32_e32 v196, v70, v192
	v_mul_f32_e32 v197, v71, v193
	v_mul_f32_e32 v198, v72, v194
	v_mul_f32_e32 v199, v73, v195
	v_lshl_add_u64 v[202:203], v[184:185], 0, v[208:209]
	v_cvt_pk_bf16_f32 v200, v196, v197
	v_cvt_pk_bf16_f32 v201, v198, v199
	s_nop 0
	global_store_dwordx2 v[202:203], v[200:201], off
	v_mul_f32_e64 v192, v188, |v171|
	v_mul_f32_e64 v193, v189, |v171|
	v_mul_f32_e64 v194, v190, |v171|
	v_mul_f32_e64 v195, v191, |v171|
	v_mul_f32_e32 v192, 0x3fb8aa3b, v192
	v_mul_f32_e32 v193, 0x3fb8aa3b, v193
	v_mul_f32_e32 v194, 0x3fb8aa3b, v194
	v_mul_f32_e32 v195, 0x3fb8aa3b, v195
	v_exp_f32_e32 v192, v192
	v_exp_f32_e32 v193, v193
	v_exp_f32_e32 v194, v194
	v_exp_f32_e32 v195, v195
	s_nop 0
	v_mul_f32_e32 v196, v66, v192
	v_mul_f32_e32 v197, v67, v193
	v_mul_f32_e32 v198, v68, v194
	v_mul_f32_e32 v199, v69, v195
	v_lshl_add_u64 v[202:203], v[186:187], 0, v[208:209]
	v_cvt_pk_bf16_f32 v200, v196, v197
	v_cvt_pk_bf16_f32 v201, v198, v199
	s_nop 0
	global_store_dwordx2 v[202:203], v[200:201], off
	v_or_b32_e32 v206, 32, v130
	v_cvt_f32_i32_e32 v188, v206
	v_or_b32_e32 v204, 1, v206
	v_cvt_f32_i32_e32 v189, v204
	v_or_b32_e32 v204, 2, v206
	v_cvt_f32_i32_e32 v190, v204
	v_or_b32_e32 v204, 3, v206
	v_cvt_f32_i32_e32 v191, v204
	v_mul_f32_e32 v188, 0xba001002, v188
	v_mul_f32_e32 v189, 0xba001002, v189
	v_mul_f32_e32 v190, 0xba001002, v190
	v_mul_f32_e32 v191, 0xba001002, v191
	v_lshlrev_b32_e32 v208, 1, v206
	v_add_u32_e32 v208, 0x1000, v208
	v_mul_f32_e64 v192, v188, |v164|
	v_mul_f32_e64 v193, v189, |v164|
	v_mul_f32_e64 v194, v190, |v164|
	v_mul_f32_e64 v195, v191, |v164|
	v_mul_f32_e32 v192, 0x3fb8aa3b, v192
	v_mul_f32_e32 v193, 0x3fb8aa3b, v193
	v_mul_f32_e32 v194, 0x3fb8aa3b, v194
	v_mul_f32_e32 v195, 0x3fb8aa3b, v195
	v_exp_f32_e32 v192, v192
	v_exp_f32_e32 v193, v193
	v_exp_f32_e32 v194, v194
	v_exp_f32_e32 v195, v195
	s_nop 0
	v_mul_f32_e32 v196, v62, v192
	v_mul_f32_e32 v197, v63, v193
	v_mul_f32_e32 v198, v64, v194
	v_mul_f32_e32 v199, v65, v195
	v_lshl_add_u64 v[202:203], v[172:173], 0, v[208:209]
	v_cvt_pk_bf16_f32 v200, v196, v197
	v_cvt_pk_bf16_f32 v201, v198, v199
	s_nop 0
	global_store_dwordx2 v[202:203], v[200:201], off
	v_mul_f32_e64 v192, v188, |v165|
	v_mul_f32_e64 v193, v189, |v165|
	v_mul_f32_e64 v194, v190, |v165|
	v_mul_f32_e64 v195, v191, |v165|
	v_mul_f32_e32 v192, 0x3fb8aa3b, v192
	v_mul_f32_e32 v193, 0x3fb8aa3b, v193
	v_mul_f32_e32 v194, 0x3fb8aa3b, v194
	v_mul_f32_e32 v195, 0x3fb8aa3b, v195
	v_exp_f32_e32 v192, v192
	v_exp_f32_e32 v193, v193
	v_exp_f32_e32 v194, v194
	v_exp_f32_e32 v195, v195
	s_nop 0
	v_mul_f32_e32 v196, v58, v192
	v_mul_f32_e32 v197, v59, v193
	v_mul_f32_e32 v198, v60, v194
	v_mul_f32_e32 v199, v61, v195
	v_lshl_add_u64 v[202:203], v[174:175], 0, v[208:209]
	v_cvt_pk_bf16_f32 v200, v196, v197
	v_cvt_pk_bf16_f32 v201, v198, v199
	s_nop 0
	global_store_dwordx2 v[202:203], v[200:201], off
	v_mul_f32_e64 v192, v188, |v166|
	v_mul_f32_e64 v193, v189, |v166|
	v_mul_f32_e64 v194, v190, |v166|
	v_mul_f32_e64 v195, v191, |v166|
	v_mul_f32_e32 v192, 0x3fb8aa3b, v192
	v_mul_f32_e32 v193, 0x3fb8aa3b, v193
	v_mul_f32_e32 v194, 0x3fb8aa3b, v194
	v_mul_f32_e32 v195, 0x3fb8aa3b, v195
	v_exp_f32_e32 v192, v192
	v_exp_f32_e32 v193, v193
	v_exp_f32_e32 v194, v194
	v_exp_f32_e32 v195, v195
; __device__ __forceinline__ bf16_t f2bf(float f) { return (bf16_t)(pack2(f, f) & 0xffffu); }
;   __device__ __forceinline__ void r4(int g, int rig, int col, f32x4 v) const {
;     const int c = col & 1023; const bool bwd = col >= 1024;
;     const float dec = fabsf(decay[c]);
;     bf16_t* rp = Rf + (size_t)c * 4096;
; #pragma unroll
;     for (int j = 0; j < 4; ++j) {
;       const int t = rig + j;
;       const float val = v[j] * __expf(-(float)t * (1.0f / 2047.0f) * dec);
;       if (!bwd) rp[2048 - t] = f2bf(val);
;       else if (t > 0) rp[2048 + t] = f2bf(val);
;       else rp[0] = 0;
;     }
;   }
	s_nop 0
	v_mul_f32_e32 v196, v54, v192
	v_mul_f32_e32 v197, v55, v193
	v_mul_f32_e32 v198, v56, v194
	v_mul_f32_e32 v199, v57, v195
	v_lshl_add_u64 v[202:203], v[176:177], 0, v[208:209]
	v_cvt_pk_bf16_f32 v200, v196, v197
	v_cvt_pk_bf16_f32 v201, v198, v199
	s_nop 0
	global_store_dwordx2 v[202:203], v[200:201], off
	v_mul_f32_e64 v192, v188, |v167|
	v_mul_f32_e64 v193, v189, |v167|
	v_mul_f32_e64 v194, v190, |v167|
	v_mul_f32_e64 v195, v191, |v167|
	v_mul_f32_e32 v192, 0x3fb8aa3b, v192
	v_mul_f32_e32 v193, 0x3fb8aa3b, v193
	v_mul_f32_e32 v194, 0x3fb8aa3b, v194
	v_mul_f32_e32 v195, 0x3fb8aa3b, v195
	v_exp_f32_e32 v192, v192
	v_exp_f32_e32 v193, v193
	v_exp_f32_e32 v194, v194
	v_exp_f32_e32 v195, v195
	s_nop 0
	v_mul_f32_e32 v196, v50, v192
	v_mul_f32_e32 v197, v51, v193
	v_mul_f32_e32 v198, v52, v194
	v_mul_f32_e32 v199, v53, v195
	v_lshl_add_u64 v[202:203], v[178:179], 0, v[208:209]
	v_cvt_pk_bf16_f32 v200, v196, v197
	v_cvt_pk_bf16_f32 v201, v198, v199
	s_nop 0
	global_store_dwordx2 v[202:203], v[200:201], off
	v_mul_f32_e64 v192, v188, |v168|
	v_mul_f32_e64 v193, v189, |v168|
	v_mul_f32_e64 v194, v190, |v168|
	v_mul_f32_e64 v195, v191, |v168|
	v_mul_f32_e32 v192, 0x3fb8aa3b, v192
	v_mul_f32_e32 v193, 0x3fb8aa3b, v193
	v_mul_f32_e32 v194, 0x3fb8aa3b, v194
	v_mul_f32_e32 v195, 0x3fb8aa3b, v195
	v_exp_f32_e32 v192, v192
	v_exp_f32_e32 v193, v193
	v_exp_f32_e32 v194, v194
	v_exp_f32_e32 v195, v195
	s_nop 0
	v_mul_f32_e32 v196, v46, v192
	v_mul_f32_e32 v197, v47, v193
	v_mul_f32_e32 v198, v48, v194
	v_mul_f32_e32 v199, v49, v195
	v_lshl_add_u64 v[202:203], v[180:181], 0, v[208:209]
	v_cvt_pk_bf16_f32 v200, v196, v197
	v_cvt_pk_bf16_f32 v201, v198, v199
	s_nop 0
	global_store_dwordx2 v[202:203], v[200:201], off
	v_mul_f32_e64 v192, v188, |v169|
	v_mul_f32_e64 v193, v189, |v169|
	v_mul_f32_e64 v194, v190, |v169|
	v_mul_f32_e64 v195, v191, |v169|
	v_mul_f32_e32 v192, 0x3fb8aa3b, v192
	v_mul_f32_e32 v193, 0x3fb8aa3b, v193
	v_mul_f32_e32 v194, 0x3fb8aa3b, v194
	v_mul_f32_e32 v195, 0x3fb8aa3b, v195
	v_exp_f32_e32 v192, v192
	v_exp_f32_e32 v193, v193
	v_exp_f32_e32 v194, v194
	v_exp_f32_e32 v195, v195
	s_nop 0
	v_mul_f32_e32 v196, v42, v192
	v_mul_f32_e32 v197, v43, v193
	v_mul_f32_e32 v198, v44, v194
	v_mul_f32_e32 v199, v45, v195
	v_lshl_add_u64 v[202:203], v[182:183], 0, v[208:209]
	v_cvt_pk_bf16_f32 v200, v196, v197
	v_cvt_pk_bf16_f32 v201, v198, v199
	s_nop 0
	global_store_dwordx2 v[202:203], v[200:201], off
	v_mul_f32_e64 v192, v188, |v170|
	v_mul_f32_e64 v193, v189, |v170|
	v_mul_f32_e64 v194, v190, |v170|
	v_mul_f32_e64 v195, v191, |v170|
	v_mul_f32_e32 v192, 0x3fb8aa3b, v192
	v_mul_f32_e32 v193, 0x3fb8aa3b, v193
	v_mul_f32_e32 v194, 0x3fb8aa3b, v194
	v_mul_f32_e32 v195, 0x3fb8aa3b, v195
	v_exp_f32_e32 v192, v192
	v_exp_f32_e32 v193, v193
	v_exp_f32_e32 v194, v194
	v_exp_f32_e32 v195, v195
	s_nop 0
	v_mul_f32_e32 v196, v38, v192
	v_mul_f32_e32 v197, v39, v193
	v_mul_f32_e32 v198, v40, v194
	v_mul_f32_e32 v199, v41, v195
	v_lshl_add_u64 v[202:203], v[184:185], 0, v[208:209]
	v_cvt_pk_bf16_f32 v200, v196, v197
	v_cvt_pk_bf16_f32 v201, v198, v199
	s_nop 0
	global_store_dwordx2 v[202:203], v[200:201], off
	v_mul_f32_e64 v192, v188, |v171|
	v_mul_f32_e64 v193, v189, |v171|
	v_mul_f32_e64 v194, v190, |v171|
	v_mul_f32_e64 v195, v191, |v171|
	v_mul_f32_e32 v192, 0x3fb8aa3b, v192
	v_mul_f32_e32 v193, 0x3fb8aa3b, v193
	v_mul_f32_e32 v194, 0x3fb8aa3b, v194
	v_mul_f32_e32 v195, 0x3fb8aa3b, v195
	v_exp_f32_e32 v192, v192
	v_exp_f32_e32 v193, v193
	v_exp_f32_e32 v194, v194
	v_exp_f32_e32 v195, v195
	s_nop 0
	v_mul_f32_e32 v196, v34, v192
	v_mul_f32_e32 v197, v35, v193
	v_mul_f32_e32 v198, v36, v194
	v_mul_f32_e32 v199, v37, v195
	v_lshl_add_u64 v[202:203], v[186:187], 0, v[208:209]
	v_cvt_pk_bf16_f32 v200, v196, v197
	v_cvt_pk_bf16_f32 v201, v198, v199
	s_nop 0
	global_store_dwordx2 v[202:203], v[200:201], off
	v_or_b32_e32 v206, 48, v130
	v_cvt_f32_i32_e32 v188, v206
	v_or_b32_e32 v204, 1, v206
	v_cvt_f32_i32_e32 v189, v204
	v_or_b32_e32 v204, 2, v206
	v_cvt_f32_i32_e32 v190, v204
	v_or_b32_e32 v204, 3, v206
	v_cvt_f32_i32_e32 v191, v204
	v_mul_f32_e32 v188, 0xba001002, v188
	v_mul_f32_e32 v189, 0xba001002, v189
	v_mul_f32_e32 v190, 0xba001002, v190
	v_mul_f32_e32 v191, 0xba001002, v191
	v_lshlrev_b32_e32 v208, 1, v206
	v_add_u32_e32 v208, 0x1000, v208
	v_mul_f32_e64 v192, v188, |v164|
	v_mul_f32_e64 v193, v189, |v164|
	v_mul_f32_e64 v194, v190, |v164|
	v_mul_f32_e64 v195, v191, |v164|
	v_mul_f32_e32 v192, 0x3fb8aa3b, v192
	v_mul_f32_e32 v193, 0x3fb8aa3b, v193
	v_mul_f32_e32 v194, 0x3fb8aa3b, v194
	v_mul_f32_e32 v195, 0x3fb8aa3b, v195
	v_exp_f32_e32 v192, v192
	v_exp_f32_e32 v193, v193
	v_exp_f32_e32 v194, v194
	v_exp_f32_e32 v195, v195
	s_nop 0
	v_mul_f32_e32 v196, v30, v192
	v_mul_f32_e32 v197, v31, v193
	v_mul_f32_e32 v198, v32, v194
	v_mul_f32_e32 v199, v33, v195
	v_lshl_add_u64 v[202:203], v[172:173], 0, v[208:209]
	v_cvt_pk_bf16_f32 v200, v196, v197
	v_cvt_pk_bf16_f32 v201, v198, v199
	s_nop 0
	global_store_dwordx2 v[202:203], v[200:201], off
; __device__ __forceinline__ bf16_t f2bf(float f) { return (bf16_t)(pack2(f, f) & 0xffffu); }
;   __device__ __forceinline__ void r4(int g, int rig, int col, f32x4 v) const {
;     const int c = col & 1023; const bool bwd = col >= 1024;
;     const float dec = fabsf(decay[c]);
;     bf16_t* rp = Rf + (size_t)c * 4096;
; #pragma unroll
;     for (int j = 0; j < 4; ++j) {
;       const int t = rig + j;
;       const float val = v[j] * __expf(-(float)t * (1.0f / 2047.0f) * dec);
;       if (!bwd) rp[2048 - t] = f2bf(val);
;       else if (t > 0) rp[2048 + t] = f2bf(val);
;       else rp[0] = 0;
;     }
;   }
	v_mul_f32_e64 v192, v188, |v165|
	v_mul_f32_e64 v193, v189, |v165|
	v_mul_f32_e64 v194, v190, |v165|
	v_mul_f32_e64 v195, v191, |v165|
	v_mul_f32_e32 v192, 0x3fb8aa3b, v192
	v_mul_f32_e32 v193, 0x3fb8aa3b, v193
	v_mul_f32_e32 v194, 0x3fb8aa3b, v194
	v_mul_f32_e32 v195, 0x3fb8aa3b, v195
	v_exp_f32_e32 v192, v192
	v_exp_f32_e32 v193, v193
	v_exp_f32_e32 v194, v194
	v_exp_f32_e32 v195, v195
	s_nop 0
	v_mul_f32_e32 v196, v26, v192
	v_mul_f32_e32 v197, v27, v193
	v_mul_f32_e32 v198, v28, v194
	v_mul_f32_e32 v199, v29, v195
	v_lshl_add_u64 v[202:203], v[174:175], 0, v[208:209]
	v_cvt_pk_bf16_f32 v200, v196, v197
	v_cvt_pk_bf16_f32 v201, v198, v199
	s_nop 0
	global_store_dwordx2 v[202:203], v[200:201], off
	v_mul_f32_e64 v192, v188, |v166|
	v_mul_f32_e64 v193, v189, |v166|
	v_mul_f32_e64 v194, v190, |v166|
	v_mul_f32_e64 v195, v191, |v166|
	v_mul_f32_e32 v192, 0x3fb8aa3b, v192
	v_mul_f32_e32 v193, 0x3fb8aa3b, v193
	v_mul_f32_e32 v194, 0x3fb8aa3b, v194
	v_mul_f32_e32 v195, 0x3fb8aa3b, v195
	v_exp_f32_e32 v192, v192
	v_exp_f32_e32 v193, v193
	v_exp_f32_e32 v194, v194
	v_exp_f32_e32 v195, v195
	s_nop 0
	v_mul_f32_e32 v196, v22, v192
	v_mul_f32_e32 v197, v23, v193
	v_mul_f32_e32 v198, v24, v194
	v_mul_f32_e32 v199, v25, v195
	v_lshl_add_u64 v[202:203], v[176:177], 0, v[208:209]
	v_cvt_pk_bf16_f32 v200, v196, v197
	v_cvt_pk_bf16_f32 v201, v198, v199
	s_nop 0
	global_store_dwordx2 v[202:203], v[200:201], off
	v_mul_f32_e64 v192, v188, |v167|
	v_mul_f32_e64 v193, v189, |v167|
	v_mul_f32_e64 v194, v190, |v167|
	v_mul_f32_e64 v195, v191, |v167|
	v_mul_f32_e32 v192, 0x3fb8aa3b, v192
	v_mul_f32_e32 v193, 0x3fb8aa3b, v193
	v_mul_f32_e32 v194, 0x3fb8aa3b, v194
	v_mul_f32_e32 v195, 0x3fb8aa3b, v195
	v_exp_f32_e32 v192, v192
	v_exp_f32_e32 v193, v193
	v_exp_f32_e32 v194, v194
	v_exp_f32_e32 v195, v195
	s_nop 0
	v_mul_f32_e32 v196, v18, v192
	v_mul_f32_e32 v197, v19, v193
	v_mul_f32_e32 v198, v20, v194
	v_mul_f32_e32 v199, v21, v195
	v_lshl_add_u64 v[202:203], v[178:179], 0, v[208:209]
	v_cvt_pk_bf16_f32 v200, v196, v197
	v_cvt_pk_bf16_f32 v201, v198, v199
	s_nop 0
	global_store_dwordx2 v[202:203], v[200:201], off
	v_mul_f32_e64 v192, v188, |v168|
	v_mul_f32_e64 v193, v189, |v168|
	v_mul_f32_e64 v194, v190, |v168|
	v_mul_f32_e64 v195, v191, |v168|
	v_mul_f32_e32 v192, 0x3fb8aa3b, v192
	v_mul_f32_e32 v193, 0x3fb8aa3b, v193
	v_mul_f32_e32 v194, 0x3fb8aa3b, v194
	v_mul_f32_e32 v195, 0x3fb8aa3b, v195
	v_exp_f32_e32 v192, v192
	v_exp_f32_e32 v193, v193
	v_exp_f32_e32 v194, v194
	v_exp_f32_e32 v195, v195
	s_nop 0
	v_mul_f32_e32 v196, v14, v192
	v_mul_f32_e32 v197, v15, v193
	v_mul_f32_e32 v198, v16, v194
	v_mul_f32_e32 v199, v17, v195
	v_lshl_add_u64 v[202:203], v[180:181], 0, v[208:209]
	v_cvt_pk_bf16_f32 v200, v196, v197
	v_cvt_pk_bf16_f32 v201, v198, v199
	s_nop 0
	global_store_dwordx2 v[202:203], v[200:201], off
	v_mul_f32_e64 v192, v188, |v169|
	v_mul_f32_e64 v193, v189, |v169|
	v_mul_f32_e64 v194, v190, |v169|
	v_mul_f32_e64 v195, v191, |v169|
	v_mul_f32_e32 v192, 0x3fb8aa3b, v192
	v_mul_f32_e32 v193, 0x3fb8aa3b, v193
	v_mul_f32_e32 v194, 0x3fb8aa3b, v194
	v_mul_f32_e32 v195, 0x3fb8aa3b, v195
	v_exp_f32_e32 v192, v192
	v_exp_f32_e32 v193, v193
	v_exp_f32_e32 v194, v194
	v_exp_f32_e32 v195, v195
	s_nop 0
	v_mul_f32_e32 v196, v10, v192
	v_mul_f32_e32 v197, v11, v193
	v_mul_f32_e32 v198, v12, v194
	v_mul_f32_e32 v199, v13, v195
	v_lshl_add_u64 v[202:203], v[182:183], 0, v[208:209]
	v_cvt_pk_bf16_f32 v200, v196, v197
	v_cvt_pk_bf16_f32 v201, v198, v199
	s_nop 0
	global_store_dwordx2 v[202:203], v[200:201], off
	v_mul_f32_e64 v192, v188, |v170|
	v_mul_f32_e64 v193, v189, |v170|
	v_mul_f32_e64 v194, v190, |v170|
	v_mul_f32_e64 v195, v191, |v170|
	v_mul_f32_e32 v192, 0x3fb8aa3b, v192
	v_mul_f32_e32 v193, 0x3fb8aa3b, v193
	v_mul_f32_e32 v194, 0x3fb8aa3b, v194
	v_mul_f32_e32 v195, 0x3fb8aa3b, v195
	v_exp_f32_e32 v192, v192
	v_exp_f32_e32 v193, v193
	v_exp_f32_e32 v194, v194
	v_exp_f32_e32 v195, v195
	s_nop 0
	v_mul_f32_e32 v196, v6, v192
	v_mul_f32_e32 v197, v7, v193
	v_mul_f32_e32 v198, v8, v194
	v_mul_f32_e32 v199, v9, v195
	v_lshl_add_u64 v[202:203], v[184:185], 0, v[208:209]
	v_cvt_pk_bf16_f32 v200, v196, v197
	v_cvt_pk_bf16_f32 v201, v198, v199
	s_nop 0
	global_store_dwordx2 v[202:203], v[200:201], off
	v_mul_f32_e64 v192, v188, |v171|
	v_mul_f32_e64 v193, v189, |v171|
	v_mul_f32_e64 v194, v190, |v171|
	v_mul_f32_e64 v195, v191, |v171|
	v_mul_f32_e32 v192, 0x3fb8aa3b, v192
	v_mul_f32_e32 v193, 0x3fb8aa3b, v193
	v_mul_f32_e32 v194, 0x3fb8aa3b, v194
	v_mul_f32_e32 v195, 0x3fb8aa3b, v195
	v_exp_f32_e32 v192, v192
	v_exp_f32_e32 v193, v193
	v_exp_f32_e32 v194, v194
	v_exp_f32_e32 v195, v195
	s_nop 0
	v_mul_f32_e32 v196, v2, v192
	v_mul_f32_e32 v197, v3, v193
	v_mul_f32_e32 v198, v4, v194
	v_mul_f32_e32 v199, v5, v195
	v_lshl_add_u64 v[202:203], v[186:187], 0, v[208:209]
	v_cvt_pk_bf16_f32 v200, v196, v197
	v_cvt_pk_bf16_f32 v201, v198, v199
	s_nop 0
	global_store_dwordx2 v[202:203], v[200:201], off
.Lfilt_done:
	s_mov_b64 s[8:9], exec
	s_branch .LBB0_495
